# hot loop headers (six GEMM K-loops, attention loops, indexer score loop, memory-attention QK loop) padded to 64-byte lines
# speedup vs baseline: 1.0162x; 1.0162x over previous
;   __device__ __forceinline__ bool next(int i,AttnUnit&u)const{ if(i>=2)return false; const int s=vcu&15; u.bh=vcu>>4; u.qb=(i==0)?s:31-s; return true; }
;     __device__ __forceinline__ bool next(int i, attn_body::AttnUnit& u) const { if (i >= n) return false; const int s = v & 15; u.bh = v >> 4; u.qb = (i0 + i == 0) ? s : 31 - s; return true; }
; template <class Epi, class Sched, bool ALIGN_EPI = false, bool SP2 = false>
; __device__ __forceinline__ void gemm_phase(PG8_LAS unsigned char* lds, const Gemm g, const Sched& S, const Epi& E) {
;     ...
;         const bool has_next = S.next(ui + 1, nxt);
;         const char* nA = has_next ? (const char*)g.A + (size_t)nxt.pm * tstep : cA; const char* nB = has_next ? (const char*)g.Bt + (size_t)nxt.pn * tstep : cB;
;         for (int t = 0; t < nt; t += 2) {
;             const bool last = (t == nt - 2);
;             const char* a1 = cA + (size_t)(t + 1) * kstep;
;             const char* a2 = last ? nA : cA + (size_t)(t + 2) * kstep; const char* b2 = last ? nB : cB + (size_t)(t + 2) * kstep;
;             const char* a3 = a2 + kstep; const char* b3 = b2 + kstep;
;             if (last && has_next) S.a_ready(nxt);
;     ...
; #pragma unroll
;         for (int a = 0; a < 2; ++a)
; #pragma unroll
;             for (int b = 0; b < 2; ++b)
; #pragma unroll
;                 for (int m = 0; m < 4; ++m)
; #pragma unroll
;                     for (int n = 0; n < 2; ++n) acc[a][b][m][n] = (f32x4){0.f, 0.f, 0.f, 0.f};
;         cur = nxt; cA = nA; cB = nB; ++ui;
.LBB0_326:
	s_ashr_i32 s55, s54, 31
	s_lshl_b64 s[16:17], s[54:55], 19
	s_add_u32 s96, s59, s16
	s_addc_u32 s97, s80, s17
	s_and_b64 s[16:17], s[4:5], exec
	s_cselect_b32 s9, s97, s7
	s_cselect_b32 s11, s96, s6
	s_ashr_i32 s69, s68, 31
	s_lshl_b64 s[16:17], s[68:69], 19
	s_add_u32 s70, s81, s16
	s_addc_u32 s71, s82, s17
	s_and_b64 s[16:17], s[4:5], exec
	s_cselect_b32 s18, s71, s13
	s_cselect_b32 s20, s70, s12
	s_add_u32 s6, s6, 0x40080
	s_addc_u32 s7, s7, 0
	s_add_u32 s21, s12, 0x100
	v_mov_b32_e32 v0, 0
	s_addc_u32 s26, s13, 0
	s_mov_b32 s27, -2
	v_mov_b32_e32 v1, v0
	v_mov_b32_e32 v2, v0
	v_mov_b32_e32 v3, v0
	v_mov_b32_e32 v4, v0
	v_mov_b32_e32 v5, v0
	v_mov_b32_e32 v6, v0
	v_mov_b32_e32 v7, v0
	v_mov_b32_e32 v16, v0
	v_mov_b32_e32 v17, v0
	v_mov_b32_e32 v18, v0
	v_mov_b32_e32 v19, v0
	v_mov_b32_e32 v20, v0
	v_mov_b32_e32 v21, v0
	v_mov_b32_e32 v22, v0
	v_mov_b32_e32 v23, v0
	v_mov_b32_e32 v32, v0
	v_mov_b32_e32 v33, v0
	v_mov_b32_e32 v34, v0
	v_mov_b32_e32 v35, v0
	v_mov_b32_e32 v36, v0
	v_mov_b32_e32 v37, v0
	v_mov_b32_e32 v38, v0
	v_mov_b32_e32 v39, v0
	v_mov_b32_e32 v48, v0
	v_mov_b32_e32 v49, v0
	v_mov_b32_e32 v50, v0
	v_mov_b32_e32 v51, v0
	v_mov_b32_e32 v52, v0
	v_mov_b32_e32 v53, v0
	v_mov_b32_e32 v54, v0
	v_mov_b32_e32 v55, v0
	v_mov_b32_e32 v8, v0
	v_mov_b32_e32 v9, v0
	v_mov_b32_e32 v10, v0
	v_mov_b32_e32 v11, v0
	v_mov_b32_e32 v12, v0
	v_mov_b32_e32 v13, v0
	v_mov_b32_e32 v14, v0
	v_mov_b32_e32 v15, v0
	v_mov_b32_e32 v24, v0
	v_mov_b32_e32 v25, v0
	v_mov_b32_e32 v26, v0
	v_mov_b32_e32 v27, v0
	v_mov_b32_e32 v28, v0
	v_mov_b32_e32 v29, v0
	v_mov_b32_e32 v30, v0
	v_mov_b32_e32 v31, v0
	v_mov_b32_e32 v40, v0
	v_mov_b32_e32 v41, v0
	v_mov_b32_e32 v42, v0
	v_mov_b32_e32 v43, v0
	v_mov_b32_e32 v44, v0
	v_mov_b32_e32 v45, v0
	v_mov_b32_e32 v46, v0
	v_mov_b32_e32 v47, v0
	v_mov_b32_e32 v56, v0
	v_mov_b32_e32 v57, v0
	v_mov_b32_e32 v58, v0
	v_mov_b32_e32 v59, v0
	v_mov_b32_e32 v60, v0
	v_mov_b32_e32 v61, v0
	v_mov_b32_e32 v62, v0
	v_mov_b32_e32 v63, v0
	v_mov_b32_e32 v64, v0
	v_mov_b32_e32 v65, v0
	v_mov_b32_e32 v66, v0
	v_mov_b32_e32 v67, v0
	v_mov_b32_e32 v68, v0
	v_mov_b32_e32 v69, v0
	v_mov_b32_e32 v70, v0
	v_mov_b32_e32 v71, v0
	v_mov_b32_e32 v80, v0
	v_mov_b32_e32 v81, v0
	v_mov_b32_e32 v82, v0
	v_mov_b32_e32 v83, v0
	v_mov_b32_e32 v84, v0
	v_mov_b32_e32 v85, v0
	v_mov_b32_e32 v86, v0
	v_mov_b32_e32 v87, v0
	v_mov_b32_e32 v96, v0
	v_mov_b32_e32 v97, v0
	v_mov_b32_e32 v98, v0
	v_mov_b32_e32 v99, v0
	v_mov_b32_e32 v100, v0
	v_mov_b32_e32 v101, v0
	v_mov_b32_e32 v102, v0
	v_mov_b32_e32 v103, v0
	v_mov_b32_e32 v112, v0
	v_mov_b32_e32 v113, v0
	v_mov_b32_e32 v114, v0
	v_mov_b32_e32 v115, v0
	v_mov_b32_e32 v116, v0
	v_mov_b32_e32 v117, v0
	v_mov_b32_e32 v118, v0
	v_mov_b32_e32 v119, v0
	v_mov_b32_e32 v72, v0
	v_mov_b32_e32 v73, v0
	v_mov_b32_e32 v74, v0
	v_mov_b32_e32 v75, v0
	v_mov_b32_e32 v76, v0
	v_mov_b32_e32 v77, v0
	v_mov_b32_e32 v78, v0
	v_mov_b32_e32 v79, v0
	v_mov_b32_e32 v88, v0
	v_mov_b32_e32 v89, v0
	v_mov_b32_e32 v90, v0
	v_mov_b32_e32 v91, v0
	v_mov_b32_e32 v92, v0
	v_mov_b32_e32 v93, v0
	v_mov_b32_e32 v94, v0
	v_mov_b32_e32 v95, v0
	v_mov_b32_e32 v104, v0
	v_mov_b32_e32 v105, v0
	v_mov_b32_e32 v106, v0
	v_mov_b32_e32 v107, v0
	v_mov_b32_e32 v108, v0
	v_mov_b32_e32 v109, v0
	v_mov_b32_e32 v110, v0
	v_mov_b32_e32 v111, v0
	v_mov_b32_e32 v120, v0
	v_mov_b32_e32 v121, v0
	v_mov_b32_e32 v122, v0
	v_mov_b32_e32 v123, v0
	v_mov_b32_e32 v124, v0
	v_mov_b32_e32 v125, v0
	v_mov_b32_e32 v126, v0
	v_mov_b32_e32 v127, v0
	s_nop 0
	s_nop 0
	s_nop 0
	s_nop 0
	s_nop 0
	s_nop 0
	s_nop 0
	s_nop 0

; __device__ __forceinline__ int fresh_lane() { int l; asm volatile("v_mbcnt_lo_u32_b32 %0, -1, 0\n\tv_mbcnt_hi_u32_b32 %0, -1, %0" : "=v"(l)); return l; }
; __device__ __forceinline__ void score_unit_prompt(const Ctx& C, int b, int g, unsigned char* lds) {
;     const int lane = fresh_lane(), tid = C.wave * 64 + lane, r32 = lane & 31, hi = lane >> 5;
;     const bf16_t* qib = (const bf16_t*)(C.ws + WS_QI); const bf16_t* kib = (const bf16_t*)(C.ws + WS_KI);
; #pragma unroll
;     for (int j = 0; j < 4; ++j) { const int id = tid + 512 * j, c = id >> 5, r = id & 31;
;         *(u32x4*)(lds + id * 16) = *(const u32x4*)(qib + (size_t)(b * SEQ + 32 * g + r) * 512 + c * 8); }
;     __syncthreads();
;     const int qrow0 = b * SEQ + 32 * g;
;     float w[8]; load8_f32((const float*)(C.ws + WS_IW) + (size_t)(qrow0 + r32) * 8, w);
;     float* stg = (float*)(lds + 32768 + C.wave * 8704);
;     float* sout = (float*)(C.ws + WS_SC) + (size_t)(qrow0 + (lane >> 4)) * SEQ + (lane & 15) * 4;
;     const int nt = (g >> 1) + 1;
;     const int ntp = ((32 * g + 32 + 511) >> 9) << 3;
;     const int tq = 32 * g + r32;
;     const unsigned char* qbase = lds + hi * 512 + r32 * 16;
;     const unsigned qaddr = (unsigned)(uintptr_t)qbase;
;     const bf16_t* kp0 = kib + (size_t)(b * SEQ + r32) * 64 + hi * 8;
;     bf16x8 kf[4][2];
;     { const bf16_t* kp = kp0 + (size_t)((C.wave < nt) ? C.wave : 0) * 4096;
; #pragma unroll
;       for (int d0 = 0; d0 < 4; ++d0) { kf[d0][0] = *(const bf16x8*)(kp + d0 * 16); kf[d0][1] = *(const bf16x8*)(kp + 32 * 64 + d0 * 16); } }
;     for (int kt = C.wave; kt < ntp; kt += NWAVES) {
;         bf16x8 kn[4][2];
;         { const bf16_t* kp = kp0 + (size_t)((kt + NWAVES < nt) ? kt + NWAVES : kt) * 4096;
; #pragma unroll
;           for (int d0 = 0; d0 < 4; ++d0) { kn[d0][0] = *(const bf16x8*)(kp + d0 * 16); kn[d0][1] = *(const bf16x8*)(kp + 32 * 64 + d0 * 16); } }
; __device__ __forceinline__ void ph2_scores_select(const Ctx& C, unsigned char* lds, unsigned* q, volatile LAS unsigned* slot) {
;     ...
;         } else if (it < DB + 512) {
;             const int j = it - DB, b = j & 1, g = 255 - (j >> 1);
;             score_unit_prompt(C, b, g, lds); if (PROBE_DUP == 12) score_unit_prompt(C, b, g, lds);
;             select_group_prompt(C, b, g, lds); if (PROBE_DUP == 13) select_group_prompt(C, b, g, lds);
.LBB0_785:
	s_andn2_b64 vcc, exec, s[4:5]
	s_cbranch_vccnz .LBB0_2034
	s_add_i32 s0, s2, 0xffffff80
	s_lshr_b32 s0, s0, 1
	s_and_b32 s1, s2, 1
	s_sub_i32 s10, 0xff, s0
	s_lshl_b32 s6, s1, 13
	s_lshl_b32 s7, s10, 5
	s_waitcnt vmcnt(1)
	v_mbcnt_lo_u32_b32 v3, -1, 0
	v_mbcnt_hi_u32_b32 v3, -1, v3
	s_or_b32 s4, s7, s6
	v_and_b32_e32 v2, 31, v3
	v_or_b32_e32 v4, s4, v2
	v_add_u32_e32 v5, s89, v3
	v_lshlrev_b32_e32 v0, 10, v4
	v_lshl_add_u64 v[10:11], s[78:79], 0, v[0:1]
	v_ashrrev_i32_e32 v0, 2, v5
	s_waitcnt vmcnt(0)
	v_and_b32_e32 v6, -8, v0
	v_ashrrev_i32_e32 v7, 31, v6
	v_lshl_add_u64 v[6:7], v[6:7], 1, v[10:11]
	global_load_dwordx4 v[6:9], v[6:7], off
	v_lshl_add_u32 v0, v5, 4, 0
	s_add_i32 s5, s7, 0x21f
	s_lshr_b32 s5, s5, 6
	s_and_b32 s8, s5, 0xf8
	s_cmp_ge_u32 s76, s8
	s_waitcnt vmcnt(0)
	ds_write_b128 v0, v[6:9]
	v_add_u32_e32 v0, 0x200, v5
	v_ashrrev_i32_e32 v6, 2, v0
	v_and_b32_e32 v6, -8, v6
	v_ashrrev_i32_e32 v7, 31, v6
	v_lshl_add_u64 v[6:7], v[6:7], 1, v[10:11]
	global_load_dwordx4 v[6:9], v[6:7], off
	v_lshl_add_u32 v0, v0, 4, 0
	s_waitcnt vmcnt(0)
	ds_write_b128 v0, v[6:9]
	v_add_u32_e32 v0, 0x400, v5
	v_ashrrev_i32_e32 v6, 2, v0
	v_and_b32_e32 v6, -8, v6
	v_ashrrev_i32_e32 v7, 31, v6
	v_lshl_add_u64 v[6:7], v[6:7], 1, v[10:11]
	global_load_dwordx4 v[6:9], v[6:7], off
	v_lshl_add_u32 v0, v0, 4, 0
	s_waitcnt vmcnt(0)
	ds_write_b128 v0, v[6:9]
	v_add_u32_e32 v0, 0x600, v5
	v_ashrrev_i32_e32 v5, 2, v0
	v_and_b32_e32 v6, -8, v5
	v_ashrrev_i32_e32 v7, 31, v6
	v_lshl_add_u64 v[6:7], v[6:7], 1, v[10:11]
	global_load_dwordx4 v[6:9], v[6:7], off
	v_lshl_add_u32 v0, v0, 4, 0
	s_waitcnt vmcnt(0)
	ds_write_b128 v0, v[6:9]
	s_waitcnt lgkmcnt(0)
	s_barrier
	s_cbranch_scc1 .LBB0_793
	v_ashrrev_i32_e32 v10, 5, v3
	v_lshlrev_b32_e32 v0, 5, v4
	global_load_dwordx4 v[50:53], v0, s[96:97]
	global_load_dwordx4 v[54:57], v0, s[96:97] offset:16
	v_ashrrev_i32_e32 v11, 4, v3
	v_lshlrev_b32_e32 v0, 9, v10
	v_lshlrev_b32_e32 v6, 4, v2
	v_add_u32_e32 v4, s4, v11
	v_add3_u32 v211, 0, v0, v6
	v_or_b32_e32 v0, s6, v2
	v_readlane_b32 s4, v250, 57
	v_lshlrev_b32_e32 v0, 7, v0
	v_readlane_b32 s5, v250, 58
	v_ashrrev_i32_e32 v5, 31, v4
	s_lshr_b32 s9, s10, 1
	v_lshl_add_u64 v[6:7], s[4:5], 0, v[0:1]
	v_lshlrev_b32_e32 v8, 3, v10
	v_readlane_b32 s4, v249, 0
	v_lshlrev_b64 v[4:5], 15, v[4:5]
	v_ashrrev_i32_e32 v9, 31, v8
	v_lshlrev_b32_e32 v0, 4, v3
	s_cmp_le_u32 s76, s9
	v_readlane_b32 s5, v249, 1
	v_lshl_add_u64 v[154:155], v[8:9], 1, v[6:7]
	v_lshl_add_u64 v[4:5], s[90:91], 0, v[4:5]
	v_and_b32_e32 v0, 0xf0, v0
	s_cselect_b32 s5, s5, 0
	s_cselect_b32 s4, s4, 0
	v_lshl_add_u64 v[156:157], v[4:5], 0, v[0:1]
	v_lshl_add_u64 v[4:5], s[4:5], 1, v[154:155]
	s_movk_i32 s4, 0x1000
	v_add_co_u32_e32 v6, vcc, s4, v4
	v_or_b32_e32 v212, s7, v2
	s_nop 0
	v_addc_co_u32_e32 v7, vcc, 0, v5, vcc
	global_load_dwordx4 v[90:93], v[6:7], off offset:96
	global_load_dwordx4 v[106:109], v[4:5], off offset:96
	global_load_dwordx4 v[94:97], v[6:7], off offset:64
	global_load_dwordx4 v[110:113], v[4:5], off offset:64
	global_load_dwordx4 v[98:101], v[6:7], off offset:32
	global_load_dwordx4 v[114:117], v[4:5], off offset:32
	global_load_dwordx4 v[102:105], v[6:7], off
	global_load_dwordx4 v[118:121], v[4:5], off
	v_mul_u32_u24_e32 v2, 0x110, v2
	v_lshlrev_b32_e32 v3, 4, v10
	v_readlane_b32 s4, v249, 12
	v_lshlrev_b32_e32 v213, 2, v10
	v_subrev_u32_e32 v214, 32, v212
	v_add3_u32 v215, s4, v2, v3
	v_add_u32_e32 v0, s4, v0
	s_movk_i32 s4, 0x110
	v_mul_lo_u32 v2, v11, s4
	v_add_u32_e32 v216, v0, v2
	s_mov_b32 s4, s89
	s_mov_b32 s11, s76
	s_branch .LBB0_789
	s_nop 0
	s_nop 0
	s_nop 0
	s_nop 0
	s_nop 0
	s_nop 0
	s_nop 0
	s_nop 0
	s_nop 0
	s_nop 0
	s_nop 0

; #define WAIT_BAR(N) asm volatile("s_waitcnt vmcnt(" #N ") lgkmcnt(0)\n\ts_barrier":::"memory")
;   #define DMA_K(t,slot) glds16(ksrc+(long)(t)*KVBLK*DM,(unsigned)__builtin_amdgcn_readfirstlane(kdst+(slot)))
;   #define DMA_V(t,slot) glds16(vsrc+(long)(t)*KVBLK*DM,(unsigned)__builtin_amdgcn_readfirstlane(vdst+(slot)))
;   #define CMASK(P0,P1,t) do{int jb_=(t)-(NT-4); if(jb_>=0)cmask(P0,P1,jb_,qrel,hi);}while(0)
;   #define START(P0,P1) do{ resc=false; \
;     _Pragma("unroll") for(int r=0;r<16;++r)P0[r]=__builtin_amdgcn_exp2f(P0[r]); }while(0)
;   #define ROT() do{sl_prev=sl_cur;sl_cur=sl_next;sl_next=(sl_next==(NSLOT-1)*SLOTB)?0:sl_next+SLOTB;}while(0)
;   #define CMASK(P0,P1,t) do{}while(0)
;   #define CMASK(P0,P1,t) do{int jb_=(t)-(NT-4); if(jb_>=0)cmask(P0,P1,jb_,qrel,hi);}while(0)
; template<int THRL> __device__ __forceinline__ void attn_unit(int b,int h,int qb,const bf16*Q,const bf16*__restrict__ K,const bf16*__restrict__ V,bf16*O,const unsigned long long*M,char*shm,int wid_in){
;     ...
;   float l_reg=0.f;f32x16 o[2];o[0]=f32x16{};o[1]=f32x16{};
;     ...
;   qkt(pA0,pA1,Kbase,qr,f32x16{},r32,hi);asm volatile("s_nop 15\n\ts_nop 7":"+v"(pA0),"+v"(pA1));CMASK(pA0,pA1,0);
;   START(pA0,pA1);
;   _Pragma("unroll") for(int r=0;r<16;++r)pA1[r]=__builtin_amdgcn_exp2f(pA1[r]);
;   WAIT_BAR(0);
;   DMA_K(3,0);DMA_V(1,SLOTB);
;   ROT();
;   kload8(kf,kp0+sl_cur);
;   WAIT_BAR(2);
;     ...
;   int t=1;
;     ...
;   for(;t+5<NT;t+=2){
.LBB0_2678:
	s_addk_i32 s1, 0x100
	s_lshr_b32 s72, s1, 6
	s_waitcnt vmcnt(0) lgkmcnt(0)
	s_barrier
	s_nop 8
	v_exp_f32_e32 v48, v0
	v_exp_f32_e32 v49, v1
	v_lshl_add_u64 v[0:1], v[176:177], 0, s[88:89]
	s_mov_b32 s1, m0
	s_mov_b32 m0, s2
	s_nop 0
	global_load_lds_dwordx4 v[0:1], off
	s_mov_b32 m0, s1
	s_cmp_lg_u32 0, -1
	s_cselect_b32 s1, 0, 0
	v_readlane_b32 s22, v249, 20
	s_add_i32 s1, s1, s22
	v_lshl_add_u64 v[0:1], v[178:179], 0, s[80:81]
	s_add_i32 s1, s1, 0x8000
	s_mov_b32 s22, m0
	s_mov_b32 m0, s1
	s_nop 0
	global_load_lds_dwordx4 v[0:1], off
	s_mov_b32 m0, s22
	ds_read_b128 v[172:175], v190 offset:8192
	ds_read_b128 v[164:167], v190 offset:8704
	ds_read_b128 v[168:171], v190 offset:10240
	ds_read_b128 v[160:163], v190 offset:10752
	ds_read_b128 v[156:159], v190 offset:12288
	ds_read_b128 v[152:155], v190 offset:12800
	ds_read_b128 v[148:151], v190 offset:14336
	ds_read_b128 v[144:147], v190 offset:14848
	v_lshlrev_b32_e32 v33, 1, v32
	v_lshlrev_b32_e32 v32, 4, v32
	v_exp_f32_e32 v64, v16
	v_exp_f32_e32 v65, v17
	v_exp_f32_e32 v66, v18
	v_exp_f32_e32 v67, v19
	v_exp_f32_e32 v68, v20
	v_exp_f32_e32 v69, v21
	v_exp_f32_e32 v70, v22
	v_exp_f32_e32 v71, v23
	v_exp_f32_e32 v72, v24
	v_exp_f32_e32 v73, v25
	v_exp_f32_e32 v74, v26
	v_exp_f32_e32 v75, v27
	v_exp_f32_e32 v76, v28
	v_exp_f32_e32 v77, v29
	v_exp_f32_e32 v78, v30
	v_exp_f32_e32 v79, v31
	v_exp_f32_e32 v50, v2
	v_exp_f32_e32 v51, v3
	v_exp_f32_e32 v52, v4
	v_exp_f32_e32 v53, v5
	v_exp_f32_e32 v54, v6
	v_exp_f32_e32 v55, v7
	v_exp_f32_e32 v56, v8
	v_exp_f32_e32 v57, v9
	v_exp_f32_e32 v58, v10
	v_exp_f32_e32 v59, v11
	v_exp_f32_e32 v60, v12
	v_exp_f32_e32 v61, v13
	v_exp_f32_e32 v62, v14
	v_exp_f32_e32 v63, v15
	v_and_b32_e32 v192, 32, v33
	v_and_b32_e32 v32, 0xc0, v32
	s_waitcnt vmcnt(2) lgkmcnt(0)
	s_barrier
	v_lshl_or_b32 v184, v34, 8, v32
	v_add_u32_e32 v32, 0, v192
	s_mov_b32 s0, 1
	v_add3_u32 v191, v32, v189, v184
	s_mov_b32 s26, 0
	s_andn2_b64 vcc, exec, s[24:25]
	s_mov_b32 s22, 0
	s_cbranch_vccnz .LBB0_2719
	v_mov_b32_e32 v32, 0
	s_add_i32 s1, s72, -5
	s_movk_i32 s33, 0x4000
	s_movk_i32 s73, 0x2000
	s_mov_b64 s[24:25], 0
	s_mov_b64 s[28:29], s[34:35]
	v_mov_b32_e32 v0, 0
	v_mov_b32_e32 v1, v32
	v_mov_b32_e32 v2, v32
	v_mov_b32_e32 v3, v32
	v_mov_b32_e32 v4, v32
	v_mov_b32_e32 v5, v32
	v_mov_b32_e32 v6, v32
	v_mov_b32_e32 v7, v32
	v_mov_b32_e32 v8, v32
	v_mov_b32_e32 v9, v32
	v_mov_b32_e32 v10, v32
	v_mov_b32_e32 v11, v32
	v_mov_b32_e32 v12, v32
	v_mov_b32_e32 v13, v32
	v_mov_b32_e32 v14, v32
	v_mov_b32_e32 v15, v32
	v_mov_b32_e32 v16, 0
	v_mov_b32_e32 v17, v32
	v_mov_b32_e32 v18, v32
	v_mov_b32_e32 v19, v32
	v_mov_b32_e32 v20, v32
	v_mov_b32_e32 v21, v32
	v_mov_b32_e32 v22, v32
	v_mov_b32_e32 v23, v32
	v_mov_b32_e32 v24, v32
	v_mov_b32_e32 v25, v32
	v_mov_b32_e32 v26, v32
	v_mov_b32_e32 v27, v32
	v_mov_b32_e32 v28, v32
	v_mov_b32_e32 v29, v32
	v_mov_b32_e32 v30, v32
	v_mov_b32_e32 v31, v32
	s_nop 0
	s_nop 0
	s_nop 0
	s_nop 0
	s_nop 0

;   #define RESC() do{}while(0)
;   #define ROT() do{sl_prev=sl_cur;sl_cur=sl_next;sl_next=(sl_next==(NSLOT-1)*SLOTB)?0:sl_next+SLOTB;}while(0)
;   #define ENDW(tt) do{ if((tt)+3<NT){WAIT_BAR(2);} else if((tt)+2<NT){WAIT_BAR(1);} else {WAIT_BAR(0);} }while(0)
; __device__ __forceinline__ void cmask(f32x16&p0,f32x16&p1,int jb,int qrel,int hi){
;   const float NEG=-INFINITY; int kb=64*jb+4*hi;
;   #pragma unroll
;   for(int r=0;r<16;++r){int kv=kb+(r&3)+8*(r>>2); if(kv>qrel)p0[r]=NEG; if(kv+32>qrel)p1[r]=NEG;}
; }
; template<int THRL> __device__ __forceinline__ void attn_unit(int b,int h,int qb,const bf16*Q,const bf16*__restrict__ K,const bf16*__restrict__ V,bf16*O,const unsigned long long*M,char*shm,int wid_in){
;     ...
;   for(;t+1<NT;t+=2){
;     STEP(pB0,pB1,pA0,pA1,t,(t+3<NT),(t+1<NT),(t+1<NT));       ENDW(t);   RESC(); ROT();
.LBB0_2682:
	v_readlane_b32 s1, v249, 22
	s_and_b32 s1, s1, 15
	s_lshl_b32 s24, s1, 8
	s_lshl_b32 s1, s1, 2
	s_sub_i32 s47, 0, s1
	s_lshl_b32 s1, s0, 6
	v_add3_u32 v34, s1, 64, v188
	s_mov_b32 s1, s23
	v_subrev_u32_e32 v220, s24, v34
	s_add_i32 s52, s0, 2
	s_lshl_b64 s[24:25], s[0:1], 8
	s_add_u32 s24, s34, s24
	v_subrev_u32_e32 v33, 32, v187
	v_subrev_u32_e32 v193, 33, v187
	v_subrev_u32_e32 v194, 34, v187
	v_subrev_u32_e32 v195, 35, v187
	v_add_u32_e32 v196, -8, v187
	v_subrev_u32_e32 v197, 40, v187
	v_add_u32_e32 v198, -9, v187
	v_subrev_u32_e32 v199, 41, v187
	v_add_u32_e32 v200, -10, v187
	v_subrev_u32_e32 v201, 42, v187
	v_add_u32_e32 v202, -11, v187
	v_subrev_u32_e32 v203, 43, v187
	v_add_u32_e32 v204, -16, v187
	v_subrev_u32_e32 v205, 48, v187
	v_subrev_u32_e32 v206, 17, v187
	v_subrev_u32_e32 v207, 49, v187
	v_subrev_u32_e32 v208, 18, v187
	v_subrev_u32_e32 v209, 50, v187
	v_subrev_u32_e32 v210, 19, v187
	v_subrev_u32_e32 v211, 51, v187
	v_subrev_u32_e32 v212, 24, v187
	v_subrev_u32_e32 v213, 56, v187
	v_subrev_u32_e32 v214, 25, v187
	v_subrev_u32_e32 v215, 57, v187
	v_subrev_u32_e32 v216, 26, v187
	v_subrev_u32_e32 v217, 58, v187
	v_subrev_u32_e32 v218, 27, v187
	v_subrev_u32_e32 v219, 59, v187
	s_addc_u32 s25, s35, s25
	s_lshl_b64 s[28:29], s[0:1], 16
	s_nop 0

; __device__ __forceinline__ int fresh_lane() { int l; asm volatile("v_mbcnt_lo_u32_b32 %0, -1, 0\n\tv_mbcnt_hi_u32_b32 %0, -1, %0" : "=v"(l)); return l; }
; #define WAIT_BAR(N) asm volatile("s_waitcnt vmcnt(" #N ") lgkmcnt(0)\n\ts_barrier":::"memory")
;   #define DMA_K(t,slot) glds16(ksrc+(long)(t)*KVBLK*DM,(unsigned)__builtin_amdgcn_readfirstlane(kdst+(slot)))
;   #define CMASK(P0,P1,t) do{}while(0)
; template<int THRL> __device__ __forceinline__ void attn_unit(int b,int h,int qb,const bf16*Q,const bf16*__restrict__ K,const bf16*__restrict__ V,bf16*O,const unsigned long long*M,char*shm,int wid_in){
;   const int lane=fresh_lane(),r32=lane&31,hi=lane>>5; const int wid=wid_in;
;   const long rowbase=(long)b*SEQ; const int q0=qb*QB;
;   const bf16*Qw=Q+(rowbase+q0+wid*QBLK)*DM+h*D;
;   const bf16*Kh=K+rowbase*DM+h*D,*Vh=V+rowbase*DM+h*D;
;   const unsigned long long*mbase=M+((size_t)(b*256+qb*8+wid))*(128*32); v16i mwA,mwB;
;   const unsigned lds0=(unsigned)(uintptr_t)shm;
;   float*wsf=(float*)(shm+LDS_WS)+wid*64;
;   const bf16*ksrc=Kh+(long)lane*DM+wid*8;
;   const bf16*vsrc=Vh+(long)(16*(wid&3)+(lane>>2))*DM+(wid>>2)*32+(lane&3)*8;
;   const unsigned kdst=lds0+LDS_K+wid*1024, vdst=lds0+LDS_V+wid*1024;
;     ...
;   const int vb0=(int)(lds0+LDS_V)+((lane>>4)&1)*32+(lane&3)*8+(4*hi+((lane&15)>>2))*64;
;   const char*Kbase=shm+LDS_K; bf16x8 kf[8];
;   const lds_cptr shm3=(lds_cptr)shm; const lds_cptr kp0=shm3+LDS_K+hi*1024+r32*16; const lds_cptr vp0=shm3+LDS_V+((lane>>4)&1)*32+(lane&3)*8+(4*hi+((lane&15)>>2))*64;
;   const int NT=(q0+QB)/KVBLK;
;   DMA_K(0,0);DMA_V(0,0);DMA_K(1,SLOTB);
;   bf16x8 qr[4];
;   #pragma unroll
;   for(int d0=0;d0<4;++d0)qr[d0]=*reinterpret_cast<const bf16x8*>(&Qw[(long)r32*DM+d0*16+hi*8]);
;   float l_reg=0.f;f32x16 o[2];o[0]=f32x16{};o[1]=f32x16{};
;   const int qrel=wid*QBLK+r32;
;     ...
;   bool resc=false;
;     ...
;   f32x16 pA0,pA1,pB0,pB1;
;   int sl_prev=0,sl_cur=0,sl_next=SLOTB;
;     ...
;   MLOAD_P0(0);
;   DMA_K(2,2*SLOTB);
;   WAIT_BAR(3);
;   qkt(pA0,pA1,Kbase,qr,f32x16{},r32,hi);asm volatile("s_nop 15\n\ts_nop 7":"+v"(pA0),"+v"(pA1));CMASK(pA0,pA1,0);
;   START(pA0,pA1);
;   _Pragma("unroll") for(int r=0;r<16;++r)pA1[r]=__builtin_amdgcn_exp2f(pA1[r]);
;   WAIT_BAR(0);
;   DMA_K(3,0);DMA_V(1,SLOTB);
;   ROT();
;   kload8(kf,kp0+sl_cur);
;   WAIT_BAR(2);
;   s16x4 vlo[8],vhi[8]; u32x4 pw0,pw1,pw2,pw3;
.LBB0_2746:
	s_xor_b32 s33, s46, 31
	s_lshl_b32 s0, s33, 8
	s_add_i32 s1, s0, s53
	s_add_u32 s20, s94, s1
	s_addc_u32 s21, s95, 0
	s_lshl_b64 s[4:5], s[20:21], 10
	s_add_u32 s1, s52, s4
	v_mbcnt_lo_u32_b32 v44, -1, 0
	v_mbcnt_hi_u32_b32 v44, -1, v44
	s_addc_u32 s5, s55, s5
	v_ashrrev_i32_e32 v45, 31, v44
	s_add_u32 s4, s1, s84
	v_lshlrev_b64 v[0:1], 10, v[44:45]
	s_addc_u32 s5, s5, s85
	s_lshl_b32 s1, s33, 3
	v_readlane_b32 s6, v249, 14
	v_lshl_add_u64 v[0:1], s[96:97], 0, v[0:1]
	s_mov_b32 s15, s23
	s_add_i32 s6, s6, s1
	v_lshl_add_u64 v[172:173], v[0:1], 0, s[14:15]
	v_ashrrev_i32_e32 v0, 2, v44
	v_readlane_b32 s1, v249, 4
	s_mov_b32 s8, s14
	v_lshlrev_b32_e32 v2, 3, v44
	v_add_u32_e32 v0, s1, v0
	v_ashrrev_i32_e32 v1, 31, v0
	v_lshlrev_b64 v[0:1], 10, v[0:1]
	s_ashr_i32 s7, s6, 31
	v_writelane_b32 v250, s8, 21
	v_lshl_add_u64 v[0:1], s[86:87], 0, v[0:1]
	s_mov_b32 s17, s23
	v_and_b32_e32 v183, 24, v2
	s_lshl_b64 s[6:7], s[6:7], 15
	v_writelane_b32 v250, s9, 22
	v_lshl_add_u64 v[0:1], v[0:1], 0, s[16:17]
	v_lshlrev_b32_e32 v184, 1, v183
	s_add_i32 s1, s0, 0x100
	s_mov_b32 s8, m0
	s_mov_b32 m0, s2
	s_nop 0
	global_load_lds_dwordx4 v[172:173], off
	s_mov_b32 m0, s8
	v_lshl_add_u64 v[174:175], v[0:1], 0, v[184:185]
	s_mov_b32 s8, m0
	s_mov_b32 m0, s74
	s_nop 0
	global_load_lds_dwordx4 v[174:175], off
	s_mov_b32 m0, s8
	s_cmp_lg_u32 0, -1
	s_cselect_b32 s8, 0, 0
	v_readlane_b32 s9, v249, 20
	v_ashrrev_i32_e32 v64, 5, v44
	v_lshl_add_u64 v[0:1], v[172:173], 0, s[80:81]
	s_add_i32 s24, s8, s9
	s_add_i32 s8, s24, 0x2000
	s_mov_b32 s9, m0
	s_mov_b32 m0, s8
	s_nop 0
	global_load_lds_dwordx4 v[0:1], off
	s_mov_b32 m0, s9
	v_lshlrev_b32_e32 v0, 3, v64
	v_and_b32_e32 v176, 31, v44
	v_ashrrev_i32_e32 v1, 31, v0
	v_lshl_add_u64 v[0:1], v[0:1], 1, s[4:5]
	v_lshlrev_b32_e32 v184, 10, v176
	v_lshl_add_u64 v[0:1], v[0:1], 0, v[184:185]
	global_load_dwordx4 v[116:119], v[0:1], off
	global_load_dwordx4 v[112:115], v[0:1], off offset:32
	global_load_dwordx4 v[108:111], v[0:1], off offset:64
	global_load_dwordx4 v[104:107], v[0:1], off offset:96
	v_readlane_b32 s4, v249, 2
	s_mov_b64 s[28:29], 0x20000
	v_lshlrev_b32_e32 v0, 10, v64
	v_lshlrev_b32_e32 v1, 4, v176
	s_add_u32 s34, s4, s6
	v_readlane_b32 s4, v249, 27
	s_mov_b32 s96, s16
	v_add3_u32 v188, 0, v0, v1
	v_lshl_add_u64 v[0:1], v[172:173], 0, s[28:29]
	s_addc_u32 s35, s4, s7
	s_add_i32 s22, s24, 0x4000
	s_load_dwordx16 s[56:71], s[34:35], 0x0
	s_load_dwordx16 s[4:19], s[34:35], 0x40
	s_mov_b32 s25, m0
	s_mov_b32 m0, s22
	s_nop 0
	global_load_lds_dwordx4 v[0:1], off
	s_mov_b32 m0, s25
	s_waitcnt vmcnt(3) lgkmcnt(0)
	s_barrier
	ds_read_b128 v[0:3], v188
	ds_read_b128 v[4:7], v188 offset:512
	ds_read_b128 v[32:35], v188 offset:2048
	ds_read_b128 v[36:39], v188 offset:2560
	s_lshr_b32 s31, s1, 6
	s_add_i32 s24, s24, 0x8000
	s_add_i32 s47, s31, -5
	v_lshlrev_b32_e32 v182, 2, v64
	s_add_u32 s26, s34, 0x200
	v_mov_b32_e32 v181, 0
	s_mov_b32 s53, 5
	s_mov_b32 s22, 1
	s_mov_b32 s52, 0
	s_movk_i32 s30, 0x2000
	s_movk_i32 s46, 0x4000
	s_addc_u32 s27, s35, 0
	s_mov_b32 s54, 7
	s_waitcnt vmcnt(3) lgkmcnt(3)
	v_mfma_f32_32x32x16_bf16 v[16:31], v[0:3], v[116:119], 0
	s_waitcnt lgkmcnt(2)
	v_mfma_f32_32x32x16_bf16 v[0:15], v[4:7], v[116:119], 0
	s_waitcnt vmcnt(2) lgkmcnt(1)
	v_mfma_f32_32x32x16_bf16 v[16:31], v[32:35], v[112:115], v[16:31]
	s_waitcnt lgkmcnt(0)
	v_mfma_f32_32x32x16_bf16 v[0:15], v[36:39], v[112:115], v[0:15]
	ds_read_b128 v[32:35], v188 offset:4096
	ds_read_b128 v[36:39], v188 offset:4608
	s_waitcnt vmcnt(1) lgkmcnt(1)
	v_mfma_f32_32x32x16_bf16 v[16:31], v[32:35], v[108:111], v[16:31]
	ds_read_b128 v[32:35], v188 offset:6656
	ds_read_b128 v[40:43], v188 offset:6144
	s_waitcnt lgkmcnt(2)
	v_mfma_f32_32x32x16_bf16 v[0:15], v[36:39], v[108:111], v[0:15]
	v_lshlrev_b32_e32 v36, 1, v44
	v_lshlrev_b32_e32 v37, 4, v44
	v_and_b32_e32 v187, 32, v36
	v_and_b32_e32 v36, 0xc0, v37
	v_lshl_or_b32 v180, v64, 8, v36
	v_add_u32_e32 v36, 0, v187
	v_add3_u32 v184, v36, v183, v180
	s_waitcnt vmcnt(0) lgkmcnt(0)
	v_mfma_f32_32x32x16_bf16 v[16:31], v[40:43], v[104:107], v[16:31]
	v_lshl_add_u64 v[36:37], v[172:173], 0, s[88:89]
	v_lshl_add_u64 v[40:41], v[174:175], 0, s[80:81]
	v_mfma_f32_32x32x16_bf16 v[0:15], v[32:35], v[104:107], v[0:15]
	s_nop 15
	s_nop 7
	s_waitcnt vmcnt(0) lgkmcnt(0)
	s_barrier
	s_mov_b32 s1, m0
	s_mov_b32 m0, s2
	s_nop 0
	global_load_lds_dwordx4 v[36:37], off
	s_mov_b32 m0, s1
	s_nop 0
	s_mov_b32 s1, m0
	s_mov_b32 m0, s24
	s_nop 0
	global_load_lds_dwordx4 v[40:41], off
	s_mov_b32 m0, s1
	ds_read_b128 v[156:159], v188 offset:8192
	ds_read_b128 v[148:151], v188 offset:8704
	ds_read_b128 v[152:155], v188 offset:10240
	ds_read_b128 v[144:147], v188 offset:10752
	ds_read_b128 v[140:143], v188 offset:12288
	ds_read_b128 v[136:139], v188 offset:12800
	ds_read_b128 v[132:135], v188 offset:14336
	ds_read_b128 v[128:131], v188 offset:14848
	v_exp_f32_e32 v48, v16
	v_exp_f32_e32 v49, v17
	v_exp_f32_e32 v50, v18
	v_exp_f32_e32 v51, v19
	v_exp_f32_e32 v52, v20
	v_exp_f32_e32 v53, v21
	v_exp_f32_e32 v54, v22
	v_exp_f32_e32 v55, v23
	v_exp_f32_e32 v56, v24
	v_exp_f32_e32 v57, v25
	v_exp_f32_e32 v58, v26
	v_exp_f32_e32 v59, v27
	v_exp_f32_e32 v60, v28
	v_exp_f32_e32 v61, v29
	v_exp_f32_e32 v62, v30
	v_exp_f32_e32 v63, v31
	v_exp_f32_e32 v32, v0
	v_exp_f32_e32 v33, v1
	v_exp_f32_e32 v34, v2
	v_exp_f32_e32 v35, v3
	v_exp_f32_e32 v36, v4
	v_exp_f32_e32 v37, v5
	v_exp_f32_e32 v38, v6
	v_exp_f32_e32 v39, v7
	v_exp_f32_e32 v40, v8
	v_exp_f32_e32 v41, v9
	v_exp_f32_e32 v42, v10
	v_exp_f32_e32 v43, v11
	v_exp_f32_e32 v44, v12
	v_exp_f32_e32 v45, v13
	v_exp_f32_e32 v46, v14
	v_exp_f32_e32 v47, v15
	s_waitcnt vmcnt(2) lgkmcnt(0)
	s_barrier
	v_subrev_u32_e32 v0, s0, v182
	v_add_u32_e32 v64, 0x103, v0
	s_mov_b64 s[0:1], 0
	s_mov_b64 s[24:25], s[34:35]
	v_mov_b32_e32 v0, 0
	v_mov_b32_e32 v1, v181
	v_mov_b32_e32 v2, v181
	v_mov_b32_e32 v3, v181
	v_mov_b32_e32 v4, v181
	v_mov_b32_e32 v5, v181
	v_mov_b32_e32 v6, v181
	v_mov_b32_e32 v7, v181
	v_mov_b32_e32 v8, v181
	v_mov_b32_e32 v9, v181
	v_mov_b32_e32 v10, v181
	v_mov_b32_e32 v11, v181
	v_mov_b32_e32 v12, v181
	v_mov_b32_e32 v13, v181
	v_mov_b32_e32 v14, v181
	v_mov_b32_e32 v15, v181
	v_mov_b32_e32 v16, 0
	v_mov_b32_e32 v17, v181
	v_mov_b32_e32 v18, v181
	v_mov_b32_e32 v19, v181
	v_mov_b32_e32 v20, v181
	v_mov_b32_e32 v21, v181
	v_mov_b32_e32 v22, v181
	v_mov_b32_e32 v23, v181
	v_mov_b32_e32 v24, v181
	v_mov_b32_e32 v25, v181
	v_mov_b32_e32 v26, v181
	v_mov_b32_e32 v27, v181
	v_mov_b32_e32 v28, v181
	v_mov_b32_e32 v29, v181
	v_mov_b32_e32 v30, v181
	v_mov_b32_e32 v31, v181
	s_nop 0
	s_nop 0
	s_nop 0
	s_nop 0
	s_nop 0
	s_nop 0
	s_nop 0
	s_nop 0
.LBB0_2747:
	s_mov_b32 s72, s46
	v_mov_b32_e32 v189, v64
	s_mov_b32 s44, s54
	s_mov_b64 s[86:87], s[26:27]
	s_mov_b64 s[94:95], s[28:29]
	s_mov_b32 s45, s53
	v_cndmask_b32_e64 v48, 0, v48, s[56:57]
	v_cndmask_b32_e64 v56, 0, v56, s[4:5]
	v_cndmask_b32_e64 v49, 0, v49, s[58:59]
	v_cndmask_b32_e64 v57, 0, v57, s[6:7]
	v_cndmask_b32_e64 v50, 0, v50, s[60:61]
	v_cndmask_b32_e64 v58, 0, v58, s[8:9]
	v_cndmask_b32_e64 v51, 0, v51, s[62:63]
	v_cndmask_b32_e64 v59, 0, v59, s[10:11]
	v_cndmask_b32_e64 v52, 0, v52, s[64:65]
	v_cndmask_b32_e64 v60, 0, v60, s[12:13]
	v_cndmask_b32_e64 v53, 0, v53, s[66:67]
	v_cndmask_b32_e64 v61, 0, v61, s[14:15]
	v_cndmask_b32_e64 v54, 0, v54, s[68:69]
	v_cndmask_b32_e64 v62, 0, v62, s[16:17]
	v_cndmask_b32_e64 v55, 0, v55, s[70:71]
	v_cndmask_b32_e64 v63, 0, v63, s[18:19]
	s_load_dwordx16 s[4:19], s[24:25], 0x80
	s_load_dwordx16 s[56:71], s[24:25], 0xc0
	v_add_u32_e32 v168, s52, v184
	ds_read_b64_tr_b16 v[120:121], v168 offset:24576
	ds_read_b64_tr_b16 v[122:123], v168 offset:25088
	v_add_f32_e32 v64, v48, v49
	v_add_f32_e32 v64, v64, v50
	v_add_f32_e32 v64, v64, v51
	v_add_f32_e32 v64, v64, v52
	v_add_f32_e32 v64, v64, v53
	v_cvt_pk_bf16_f32 v160, v48, v49
	v_cvt_pk_bf16_f32 v161, v50, v51
	ds_read_b64_tr_b16 v[48:49], v168 offset:28672
	ds_read_b64_tr_b16 v[50:51], v168 offset:29184
	v_add_f32_e32 v64, v54, v64
	v_add_f32_e32 v64, v55, v64
	v_add_f32_e32 v64, v56, v64
	v_add_f32_e32 v64, v57, v64
	v_cvt_pk_bf16_f32 v162, v52, v53
	v_cvt_pk_bf16_f32 v163, v54, v55
	ds_read_b64_tr_b16 v[124:125], v168 offset:25600
	ds_read_b64_tr_b16 v[126:127], v168 offset:26112
	v_add_f32_e32 v52, v58, v64
	v_add_f32_e32 v52, v59, v52
	v_add_f32_e32 v52, v60, v52
	v_add_f32_e32 v96, v61, v52
	v_cvt_pk_bf16_f32 v164, v56, v57
	v_cvt_pk_bf16_f32 v165, v58, v59
	s_waitcnt lgkmcnt(13)
	v_mfma_f32_32x32x16_bf16 v[80:95], v[156:159], v[116:119], 0
	s_waitcnt lgkmcnt(0)
	s_add_u32 s28, s24, 0x100
	s_addc_u32 s29, s25, 0
	v_cndmask_b32_e64 v32, 0, v32, s[4:5]
	v_cndmask_b32_e64 v40, 0, v40, s[56:57]
	v_cndmask_b32_e64 v33, 0, v33, s[6:7]
	v_cndmask_b32_e64 v41, 0, v41, s[58:59]
	s_waitcnt lgkmcnt(12)
	v_mfma_f32_32x32x16_bf16 v[64:79], v[148:151], v[116:119], 0
	v_cndmask_b32_e64 v34, 0, v34, s[8:9]
	v_cndmask_b32_e64 v42, 0, v42, s[60:61]
	v_cndmask_b32_e64 v35, 0, v35, s[10:11]
	v_cndmask_b32_e64 v43, 0, v43, s[62:63]
	v_cndmask_b32_e64 v36, 0, v36, s[12:13]
	v_cndmask_b32_e64 v44, 0, v44, s[64:65]
	v_cndmask_b32_e64 v37, 0, v37, s[14:15]
	v_cndmask_b32_e64 v45, 0, v45, s[66:67]
	v_cndmask_b32_e64 v38, 0, v38, s[16:17]
	v_cndmask_b32_e64 v46, 0, v46, s[68:69]
	v_cndmask_b32_e64 v39, 0, v39, s[18:19]
	v_cndmask_b32_e64 v47, 0, v47, s[70:71]
	s_load_dwordx16 s[4:19], s[28:29], 0x0
	s_waitcnt lgkmcnt(11)
	v_mfma_f32_32x32x16_bf16 v[80:95], v[152:155], v[112:115], v[80:95]
	s_load_dwordx16 s[56:71], s[28:29], 0x40
	ds_read_b64_tr_b16 v[52:53], v168 offset:29696
	ds_read_b64_tr_b16 v[54:55], v168 offset:30208
	s_waitcnt lgkmcnt(12)
	v_mfma_f32_32x32x16_bf16 v[64:79], v[144:147], v[112:115], v[64:79]
	v_add_f32_e32 v56, v62, v96
	v_add_f32_e32 v56, v63, v56
	v_add_f32_e32 v56, v56, v32
	v_add_f32_e32 v96, v56, v33
	v_cvt_pk_bf16_f32 v166, v60, v61
	v_cvt_pk_bf16_f32 v167, v62, v63
	ds_read_b64_tr_b16 v[56:57], v168 offset:26624
	ds_read_b64_tr_b16 v[58:59], v168 offset:27136
	v_add_f32_e32 v60, v34, v96
	v_add_f32_e32 v60, v35, v60
	v_add_f32_e32 v60, v36, v60
	v_add_f32_e32 v60, v37, v60
	v_cvt_pk_bf16_f32 v100, v32, v33
	v_cvt_pk_bf16_f32 v101, v34, v35
	s_waitcnt lgkmcnt(13)
	v_mfma_f32_32x32x16_bf16 v[80:95], v[140:143], v[108:111], v[80:95]
	ds_read_b64_tr_b16 v[32:33], v168 offset:30720
	ds_read_b64_tr_b16 v[34:35], v168 offset:31232
	s_waitcnt lgkmcnt(14)
	v_mfma_f32_32x32x16_bf16 v[64:79], v[136:139], v[108:111], v[64:79]
	v_add_f32_e32 v60, v38, v60
	v_add_f32_e32 v60, v39, v60
	v_add_f32_e32 v60, v40, v60
	v_add_f32_e32 v96, v41, v60
	v_cvt_pk_bf16_f32 v102, v36, v37
	v_cvt_pk_bf16_f32 v103, v38, v39
	ds_read_b64_tr_b16 v[60:61], v168 offset:27648
	ds_read_b64_tr_b16 v[62:63], v168 offset:28160
	v_add_f32_e32 v36, v42, v96
	v_add_f32_e32 v36, v43, v36
	v_add_f32_e32 v36, v44, v36
	s_waitcnt lgkmcnt(14)
	v_mfma_f32_32x32x16_bf16 v[80:95], v[132:135], v[104:107], v[80:95]
	v_add_f32_e32 v132, v45, v36
	v_cvt_pk_bf16_f32 v96, v40, v41
	v_cvt_pk_bf16_f32 v97, v42, v43
	ds_read_b64_tr_b16 v[36:37], v168 offset:31744
	ds_read_b64_tr_b16 v[38:39], v168 offset:32256
	v_mfma_f32_32x32x16_bf16 v[64:79], v[128:131], v[104:107], v[64:79]
	v_add_f32_e32 v40, v46, v132
	v_add_f32_e32 v40, v47, v40
	v_add_f32_e32 v177, 0, v40
	v_cvt_pk_bf16_f32 v98, v44, v45
	v_cvt_pk_bf16_f32 v99, v46, v47
	v_lshl_add_u64 v[168:169], v[172:173], 0, s[0:1]
	v_lshl_add_u64 v[40:41], v[168:169], 0, s[90:91]
	s_add_i32 s26, s30, s2
	s_mov_b32 s27, m0
	s_mov_b32 m0, s26
	s_nop 0
	global_load_lds_dwordx4 v[40:41], off
	s_mov_b32 m0, s27
	v_lshl_add_u64 v[170:171], v[174:175], 0, s[0:1]
	v_lshl_add_u64 v[40:41], v[170:171], 0, s[82:83]
	s_add_i32 s26, s46, s74
	s_mov_b32 s27, m0
	s_mov_b32 m0, s26
	s_nop 0
	global_load_lds_dwordx4 v[40:41], off
	s_mov_b32 m0, s27
	v_exp_f32_e32 v80, v80
	v_exp_f32_e32 v81, v81
	v_exp_f32_e32 v82, v82
	v_exp_f32_e32 v83, v83
	s_nop 0
	v_exp_f32_e32 v84, v84
	v_exp_f32_e32 v85, v85
	v_exp_f32_e32 v86, v86
	v_exp_f32_e32 v87, v87
	v_add_u32_e32 v128, s72, v188
	ds_read_b128 v[44:47], v128
	ds_read_b128 v[40:43], v128 offset:512
	v_exp_f32_e32 v88, v88
	v_exp_f32_e32 v89, v89
	v_exp_f32_e32 v90, v90
	v_exp_f32_e32 v91, v91
	ds_read_b128 v[148:151], v128 offset:2048
	ds_read_b128 v[144:147], v128 offset:2560
	v_exp_f32_e32 v92, v92
	v_exp_f32_e32 v93, v93
	v_exp_f32_e32 v94, v94
	v_exp_f32_e32 v95, v95
	ds_read_b128 v[140:143], v128 offset:4096
	ds_read_b128 v[136:139], v128 offset:4608
	v_exp_f32_e32 v64, v64
	v_exp_f32_e32 v65, v65
	v_exp_f32_e32 v66, v66
	v_exp_f32_e32 v67, v67
	ds_read_b128 v[132:135], v128 offset:6144
	ds_read_b128 v[128:131], v128 offset:6656
	v_exp_f32_e32 v68, v68
	v_exp_f32_e32 v69, v69
	v_exp_f32_e32 v70, v70
	v_exp_f32_e32 v71, v71
	s_nop 0
	v_exp_f32_e32 v72, v72
	v_exp_f32_e32 v73, v73
	v_exp_f32_e32 v74, v74
	v_exp_f32_e32 v75, v75
	s_nop 0
	v_exp_f32_e32 v76, v76
	v_exp_f32_e32 v77, v77
	v_exp_f32_e32 v78, v78
	v_exp_f32_e32 v79, v79
	s_waitcnt vmcnt(2) lgkmcnt(0)
	s_barrier
	s_add_i32 s26, s46, 0x2000
	s_waitcnt lgkmcnt(14)
	v_mfma_f32_32x32x16_bf16 v[0:15], v[160:163], v[120:123], v[0:15]
	v_cndmask_b32_e64 v80, 0, v80, s[4:5]
	v_cndmask_b32_e64 v88, 0, v88, s[56:57]
	v_cndmask_b32_e64 v81, 0, v81, s[6:7]
	v_cndmask_b32_e64 v89, 0, v89, s[58:59]
	v_cndmask_b32_e64 v82, 0, v82, s[8:9]
	v_cndmask_b32_e64 v90, 0, v90, s[60:61]
	v_cndmask_b32_e64 v83, 0, v83, s[10:11]
	v_mfma_f32_32x32x16_bf16 v[0:15], v[164:167], v[124:127], v[0:15]
	v_cndmask_b32_e64 v91, 0, v91, s[62:63]
	v_cndmask_b32_e64 v84, 0, v84, s[12:13]
	v_cndmask_b32_e64 v92, 0, v92, s[64:65]
	v_cndmask_b32_e64 v85, 0, v85, s[14:15]
	v_cndmask_b32_e64 v93, 0, v93, s[66:67]
	v_cndmask_b32_e64 v86, 0, v86, s[16:17]
	v_cndmask_b32_e64 v94, 0, v94, s[68:69]
	v_mfma_f32_32x32x16_bf16 v[0:15], v[100:103], v[56:59], v[0:15]
	v_cndmask_b32_e64 v87, 0, v87, s[18:19]
	v_cndmask_b32_e64 v95, 0, v95, s[70:71]
	s_load_dwordx16 s[4:19], s[28:29], 0x80
	s_load_dwordx16 s[56:71], s[28:29], 0xc0
	s_waitcnt lgkmcnt(10)
	v_mfma_f32_32x32x16_bf16 v[0:15], v[96:99], v[60:63], v[0:15]
	v_add_u32_e32 v178, s30, v184
	ds_read_b64_tr_b16 v[156:157], v178 offset:24576
	ds_read_b64_tr_b16 v[158:159], v178 offset:25088
	v_add_f32_e32 v56, v80, v81
	v_add_f32_e32 v56, v56, v82
	v_add_f32_e32 v56, v56, v83
	v_add_f32_e32 v56, v56, v84
	v_cvt_pk_bf16_f32 v57, v80, v81
	v_mov_b64_e32 v[124:125], v[160:161]
	v_add_f32_e32 v56, v56, v85
	v_mov_b64_e32 v[126:127], v[162:163]
	v_mov_b32_e32 v124, v57
	v_cvt_pk_bf16_f32 v125, v82, v83
	ds_read_b64_tr_b16 v[152:153], v178 offset:28672
	ds_read_b64_tr_b16 v[154:155], v178 offset:29184
	v_add_f32_e32 v56, v86, v56
	v_add_f32_e32 v56, v87, v56
	v_add_f32_e32 v56, v88, v56
	v_add_f32_e32 v56, v89, v56
	v_cvt_pk_bf16_f32 v126, v84, v85
	v_cvt_pk_bf16_f32 v127, v86, v87
	ds_read_b64_tr_b16 v[80:81], v178 offset:25600
	ds_read_b64_tr_b16 v[82:83], v178 offset:26112
	v_add_f32_e32 v56, v90, v56
	v_add_f32_e32 v56, v91, v56
	v_add_f32_e32 v56, v92, v56
	v_add_f32_e32 v179, v93, v56
	v_cvt_pk_bf16_f32 v56, v88, v89
	v_mov_b64_e32 v[120:121], v[164:165]
	v_mov_b64_e32 v[122:123], v[166:167]
	v_mov_b32_e32 v120, v56
	v_cvt_pk_bf16_f32 v121, v90, v91
	v_mfma_f32_32x32x16_bf16 v[16:31], v[160:163], v[48:51], v[16:31]
	s_waitcnt lgkmcnt(0)
	s_cmpk_lg_i32 s46, 0x4000
	s_cselect_b32 s30, s26, 0
	s_add_u32 s24, s24, 0x200
	s_addc_u32 s25, s25, 0
	v_cndmask_b32_e64 v64, 0, v64, s[4:5]
	v_cndmask_b32_e64 v72, 0, v72, s[56:57]
	v_mfma_f32_32x32x16_bf16 v[16:31], v[164:167], v[52:55], v[16:31]
	v_cndmask_b32_e64 v65, 0, v65, s[6:7]
	v_cndmask_b32_e64 v73, 0, v73, s[58:59]
	v_cndmask_b32_e64 v66, 0, v66, s[8:9]
	v_cndmask_b32_e64 v74, 0, v74, s[60:61]
	v_cndmask_b32_e64 v67, 0, v67, s[10:11]
	v_cndmask_b32_e64 v75, 0, v75, s[62:63]
	v_cndmask_b32_e64 v68, 0, v68, s[12:13]
	v_mfma_f32_32x32x16_bf16 v[16:31], v[100:103], v[32:35], v[16:31]
	v_cndmask_b32_e64 v76, 0, v76, s[64:65]
	v_cndmask_b32_e64 v69, 0, v69, s[14:15]
	v_cndmask_b32_e64 v77, 0, v77, s[66:67]
	v_cndmask_b32_e64 v70, 0, v70, s[16:17]
	v_cndmask_b32_e64 v78, 0, v78, s[68:69]
	v_cndmask_b32_e64 v71, 0, v71, s[18:19]
	v_cndmask_b32_e64 v79, 0, v79, s[70:71]
	s_waitcnt lgkmcnt(13)
	v_mfma_f32_32x32x16_bf16 v[48:63], v[44:47], v[116:119], 0
	v_add_f32_e32 v160, v181, v177
	s_load_dwordx16 s[56:71], s[24:25], 0x0
	s_load_dwordx16 s[4:19], s[24:25], 0x40
	v_mfma_f32_32x32x16_bf16 v[16:31], v[96:99], v[36:39], v[16:31]
	s_waitcnt lgkmcnt(12)
	v_mfma_f32_32x32x16_bf16 v[32:47], v[40:43], v[116:119], 0
	s_waitcnt lgkmcnt(11)
	v_mfma_f32_32x32x16_bf16 v[48:63], v[148:151], v[112:115], v[48:63]
	ds_read_b64_tr_b16 v[84:85], v178 offset:29696
	ds_read_b64_tr_b16 v[86:87], v178 offset:30208
	s_waitcnt lgkmcnt(12)
	v_mfma_f32_32x32x16_bf16 v[32:47], v[144:147], v[112:115], v[32:47]
	v_add_f32_e32 v88, v94, v179
	v_add_f32_e32 v88, v95, v88
	v_add_f32_e32 v88, v88, v64
	v_add_f32_e32 v96, v88, v65
	v_cvt_pk_bf16_f32 v122, v92, v93
	v_cvt_pk_bf16_f32 v123, v94, v95
	ds_read_b64_tr_b16 v[88:89], v178 offset:26624
	ds_read_b64_tr_b16 v[90:91], v178 offset:27136
	s_waitcnt lgkmcnt(13)
	v_mfma_f32_32x32x16_bf16 v[48:63], v[140:143], v[108:111], v[48:63]
	v_add_f32_e32 v92, v66, v96
	v_add_f32_e32 v92, v67, v92
	v_add_f32_e32 v92, v68, v92
	v_add_f32_e32 v92, v69, v92
	v_cvt_pk_bf16_f32 v100, v64, v65
	v_cvt_pk_bf16_f32 v101, v66, v67
	ds_read_b64_tr_b16 v[64:65], v178 offset:30720
	ds_read_b64_tr_b16 v[66:67], v178 offset:31232
	s_waitcnt lgkmcnt(14)
	v_mfma_f32_32x32x16_bf16 v[32:47], v[136:139], v[108:111], v[32:47]
	v_add_f32_e32 v92, v70, v92
	v_add_f32_e32 v92, v71, v92
	v_add_f32_e32 v92, v72, v92
	v_add_f32_e32 v92, v73, v92
	v_cvt_pk_bf16_f32 v102, v68, v69
	v_cvt_pk_bf16_f32 v103, v70, v71
	ds_read_b64_tr_b16 v[68:69], v178 offset:27648
	ds_read_b64_tr_b16 v[70:71], v178 offset:28160
	s_waitcnt lgkmcnt(14)
; #define WAIT_BAR(N) asm volatile("s_waitcnt vmcnt(" #N ") lgkmcnt(0)\n\ts_barrier":::"memory")
;   #define RESC() do{}while(0)
;   #define ROT() do{sl_prev=sl_cur;sl_cur=sl_next;sl_next=(sl_next==(NSLOT-1)*SLOTB)?0:sl_next+SLOTB;}while(0)
;   #define ENDW(tt) do{ if((tt)+3<NT){WAIT_BAR(2);} else if((tt)+2<NT){WAIT_BAR(1);} else {WAIT_BAR(0);} }while(0)
; template<int THRL> __device__ __forceinline__ void attn_unit(int b,int h,int qb,const bf16*Q,const bf16*__restrict__ K,const bf16*__restrict__ V,bf16*O,const unsigned long long*M,char*shm,int wid_in){
;     ...
;   int t=1;
;     ...
;   for(;t+5<NT;t+=2){
;     STEP(pB0,pB1,pA0,pA1,t,true,true,true);     WAIT_BAR(2); RESC(); ROT();
;     STEP(pA0,pA1,pB0,pB1,t+1,true,true,true);   WAIT_BAR(2); RESC(); ROT();
;   }
;     ...
;   for(;t+1<NT;t+=2){
;     STEP(pB0,pB1,pA0,pA1,t,(t+3<NT),(t+1<NT),(t+1<NT));       ENDW(t);   RESC(); ROT();
;     STEP(pA0,pA1,pB0,pB1,t+1,(t+4<NT),(t+2<NT),(t+2<NT));     ENDW(t+1); RESC(); ROT();
	v_mfma_f32_32x32x16_bf16 v[48:63], v[132:135], v[104:107], v[48:63]
	v_add_f32_e32 v92, v74, v92
	v_add_f32_e32 v92, v75, v92
	v_add_f32_e32 v92, v76, v92
	v_add_f32_e32 v92, v77, v92
	v_cvt_pk_bf16_f32 v96, v72, v73
	v_cvt_pk_bf16_f32 v97, v74, v75
	ds_read_b64_tr_b16 v[72:73], v178 offset:31744
	ds_read_b64_tr_b16 v[74:75], v178 offset:32256
	v_mfma_f32_32x32x16_bf16 v[32:47], v[128:131], v[104:107], v[32:47]
	v_add_f32_e32 v92, v78, v92
	v_add_f32_e32 v92, v79, v92
	v_add_f32_e32 v92, 0, v92
	v_cvt_pk_bf16_f32 v98, v76, v77
	v_cvt_pk_bf16_f32 v99, v78, v79
	v_lshl_add_u64 v[76:77], v[168:169], 0, s[92:93]
	s_add_i32 s26, s46, s2
	s_mov_b32 s27, m0
	s_mov_b32 m0, s26
	s_nop 0
	global_load_lds_dwordx4 v[76:77], off
	s_mov_b32 m0, s27
	v_lshl_add_u64 v[76:77], v[170:171], 0, s[88:89]
	s_add_i32 s26, s30, s74
	s_mov_b32 s27, m0
	s_mov_b32 m0, s26
	s_nop 0
	global_load_lds_dwordx4 v[76:77], off
	s_mov_b32 m0, s27
	v_add_f32_e32 v181, v160, v92
	s_add_i32 s22, s22, 2
	s_waitcnt lgkmcnt(14)
	v_mfma_f32_32x32x16_bf16 v[0:15], v[124:127], v[156:159], v[0:15]
	v_exp_f32_e32 v48, v48
	v_exp_f32_e32 v49, v49
	v_exp_f32_e32 v50, v50
	v_exp_f32_e32 v51, v51
	s_waitcnt lgkmcnt(12)
	v_mfma_f32_32x32x16_bf16 v[16:31], v[124:127], v[152:155], v[16:31]
	v_exp_f32_e32 v52, v52
	v_exp_f32_e32 v53, v53
	v_exp_f32_e32 v54, v54
	v_exp_f32_e32 v55, v55
	v_add_u32_e32 v76, s30, v188
	ds_read_b128 v[156:159], v76
	ds_read_b128 v[148:151], v76 offset:512
	s_waitcnt lgkmcnt(12)
	v_mfma_f32_32x32x16_bf16 v[0:15], v[120:123], v[80:83], v[0:15]
	v_exp_f32_e32 v56, v56
	v_exp_f32_e32 v57, v57
	v_exp_f32_e32 v58, v58
	v_exp_f32_e32 v59, v59
	ds_read_b128 v[152:155], v76 offset:2048
	ds_read_b128 v[144:147], v76 offset:2560
	s_waitcnt lgkmcnt(12)
	v_mfma_f32_32x32x16_bf16 v[16:31], v[120:123], v[84:87], v[16:31]
	v_exp_f32_e32 v60, v60
	v_exp_f32_e32 v61, v61
	v_exp_f32_e32 v62, v62
	v_exp_f32_e32 v63, v63
	ds_read_b128 v[140:143], v76 offset:4096
	ds_read_b128 v[136:139], v76 offset:4608
	s_waitcnt lgkmcnt(12)
	v_mfma_f32_32x32x16_bf16 v[0:15], v[100:103], v[88:91], v[0:15]
	v_exp_f32_e32 v32, v32
	v_exp_f32_e32 v33, v33
	v_exp_f32_e32 v34, v34
	v_exp_f32_e32 v35, v35
	ds_read_b128 v[132:135], v76 offset:6144
	ds_read_b128 v[128:131], v76 offset:6656
	s_waitcnt lgkmcnt(12)
	v_mfma_f32_32x32x16_bf16 v[16:31], v[100:103], v[64:67], v[16:31]
	v_exp_f32_e32 v36, v36
	v_exp_f32_e32 v37, v37
	v_exp_f32_e32 v38, v38
	v_exp_f32_e32 v39, v39
	s_waitcnt lgkmcnt(10)
	v_mfma_f32_32x32x16_bf16 v[0:15], v[96:99], v[68:71], v[0:15]
	v_exp_f32_e32 v40, v40
	v_exp_f32_e32 v41, v41
	v_exp_f32_e32 v42, v42
	v_exp_f32_e32 v43, v43
	s_waitcnt lgkmcnt(8)
	v_mfma_f32_32x32x16_bf16 v[16:31], v[96:99], v[72:75], v[16:31]
	v_exp_f32_e32 v44, v44
	v_exp_f32_e32 v45, v45
	v_exp_f32_e32 v46, v46
	v_exp_f32_e32 v47, v47
	s_add_i32 s26, s30, 0x2000
	s_cmpk_lg_i32 s30, 0x4000
	s_cselect_b32 s46, s26, 0
	s_add_u32 s0, s0, 0x20000
	s_addc_u32 s1, s1, 0
	s_add_i32 s54, s54, 2
	s_add_u32 s26, s86, 0x200
	s_addc_u32 s27, s87, 0
	s_waitcnt vmcnt(2) lgkmcnt(0)
	s_barrier
	s_add_u32 s28, s94, 0x20000
	s_addc_u32 s29, s95, 0
	s_add_i32 s53, s53, 2
	s_cmp_ge_u32 s22, s47
	v_add_u32_e32 v64, 0x80, v189
	s_mov_b32 s52, s72
	v_mov_b32_e32 v162, v126
	v_mov_b32_e32 v163, v127
	v_mov_b32_e32 v166, v122
	v_mov_b32_e32 v167, v123
	s_cbranch_scc0 .LBB0_2747
	s_add_i32 s0, s22, 1
	s_add_i32 s22, s31, -2
	v_readlane_b32 s53, v249, 32
	s_cmp_ge_u32 s0, s31
	s_nop 0
	v_or_b32_e32 v190, s53, v176
	s_cbranch_scc1 .LBB0_2786
	s_lshl_b32 s0, s33, 2
	v_subrev_u32_e32 v191, 32, v190
	v_subrev_u32_e32 v192, 33, v190
	v_subrev_u32_e32 v193, 34, v190
	v_subrev_u32_e32 v194, 35, v190
	v_add_u32_e32 v195, -8, v190
	v_subrev_u32_e32 v196, 40, v190
	v_add_u32_e32 v197, -9, v190
	v_subrev_u32_e32 v198, 41, v190
	v_add_u32_e32 v199, -10, v190
	v_subrev_u32_e32 v200, 42, v190
	v_add_u32_e32 v201, -11, v190
	v_subrev_u32_e32 v202, 43, v190
	v_add_u32_e32 v203, -16, v190
	v_subrev_u32_e32 v204, 48, v190
	v_subrev_u32_e32 v205, 17, v190
	v_subrev_u32_e32 v206, 49, v190
	v_subrev_u32_e32 v207, 18, v190
	v_subrev_u32_e32 v208, 50, v190
	v_subrev_u32_e32 v209, 19, v190
	v_subrev_u32_e32 v210, 51, v190
	v_subrev_u32_e32 v211, 24, v190
	v_subrev_u32_e32 v212, 56, v190
	v_subrev_u32_e32 v213, 25, v190
	v_subrev_u32_e32 v214, 57, v190
	v_subrev_u32_e32 v215, 26, v190
	v_subrev_u32_e32 v216, 58, v190
	v_subrev_u32_e32 v217, 27, v190
	v_subrev_u32_e32 v218, 59, v190
	s_sub_i32 s33, 0, s0
	v_readlane_b32 s52, v249, 31
	v_readlane_b32 s54, v249, 18
	s_nop 0
	s_nop 0
	s_nop 0
	s_nop 0
	s_nop 0
	s_nop 0
	s_nop 0
	s_nop 0

;   __device__ __forceinline__ bool next(int i,AttnUnit&u)const{ if(i>=2)return false; const int s=vcu&15; u.bh=vcu>>4; u.qb=(i==0)?s:31-s; return true; }
;     __device__ __forceinline__ bool next(int i, attn_body::AttnUnit& u) const { if (i >= n) return false; const int s = v & 15; u.bh = v >> 4; u.qb = (i0 + i == 0) ? s : 31 - s; return true; }
; template <class Epi, class Sched, bool ALIGN_EPI = false, bool SP2 = false>
; __device__ __forceinline__ void gemm_phase(PG8_LAS unsigned char* lds, const Gemm g, const Sched& S, const Epi& E) {
;     ...
;         const bool has_next = S.next(ui + 1, nxt);
;         const char* nA = has_next ? (const char*)g.A + (size_t)nxt.pm * tstep : cA; const char* nB = has_next ? (const char*)g.Bt + (size_t)nxt.pn * tstep : cB;
;         for (int t = 0; t < nt; t += 2) {
;             const bool last = (t == nt - 2);
;             const char* a1 = cA + (size_t)(t + 1) * kstep;
;             const char* a2 = last ? nA : cA + (size_t)(t + 2) * kstep; const char* b2 = last ? nB : cB + (size_t)(t + 2) * kstep;
;             const char* a3 = a2 + kstep; const char* b3 = b2 + kstep;
;             if (last && has_next) S.a_ready(nxt);
;     ...
;         for (int a = 0; a < 2; ++a)
; #pragma unroll
;             for (int b = 0; b < 2; ++b)
; #pragma unroll
;                 for (int m = 0; m < 4; ++m)
; #pragma unroll
;                     for (int n = 0; n < 2; ++n) acc[a][b][m][n] = (f32x4){0.f, 0.f, 0.f, 0.f};
;         cur = nxt; cA = nA; cB = nB; ++ui;
.LBB0_2988:
	s_ashr_i32 s29, s28, 31
	s_lshl_b64 s[30:31], s[28:29], 19
	s_add_u32 s30, s2, s30
	s_addc_u32 s31, s3, s31
	s_and_b64 s[34:35], s[4:5], exec
	s_cselect_b32 s17, s31, s39
	s_cselect_b32 s29, s30, s38
	s_ashr_i32 s25, s24, 31
	s_lshl_b64 s[34:35], s[24:25], 19
	s_add_u32 s34, s33, s34
	s_addc_u32 s35, s42, s35
	s_and_b64 s[40:41], s[4:5], exec
	s_cselect_b32 s25, s35, s27
	s_cselect_b32 s37, s34, s26
	s_add_u32 s38, s38, 0x40080
	s_addc_u32 s39, s39, 0
	s_add_u32 s52, s26, 0x100
	v_mov_b32_e32 v0, 0
	s_addc_u32 s53, s27, 0
	s_mov_b32 s62, -2
	v_mov_b32_e32 v1, v0
	v_mov_b32_e32 v2, v0
	v_mov_b32_e32 v3, v0
	v_mov_b32_e32 v4, v0
	v_mov_b32_e32 v5, v0
	v_mov_b32_e32 v6, v0
	v_mov_b32_e32 v7, v0
	v_mov_b32_e32 v16, v0
	v_mov_b32_e32 v17, v0
	v_mov_b32_e32 v18, v0
	v_mov_b32_e32 v19, v0
	v_mov_b32_e32 v20, v0
	v_mov_b32_e32 v21, v0
	v_mov_b32_e32 v22, v0
	v_mov_b32_e32 v23, v0
	v_mov_b32_e32 v32, v0
	v_mov_b32_e32 v33, v0
	v_mov_b32_e32 v34, v0
	v_mov_b32_e32 v35, v0
	v_mov_b32_e32 v36, v0
	v_mov_b32_e32 v37, v0
	v_mov_b32_e32 v38, v0
	v_mov_b32_e32 v39, v0
	v_mov_b32_e32 v48, v0
	v_mov_b32_e32 v49, v0
	v_mov_b32_e32 v50, v0
	v_mov_b32_e32 v51, v0
	v_mov_b32_e32 v52, v0
	v_mov_b32_e32 v53, v0
	v_mov_b32_e32 v54, v0
	v_mov_b32_e32 v55, v0
	v_mov_b32_e32 v8, v0
	v_mov_b32_e32 v9, v0
	v_mov_b32_e32 v10, v0
	v_mov_b32_e32 v11, v0
	v_mov_b32_e32 v12, v0
	v_mov_b32_e32 v13, v0
	v_mov_b32_e32 v14, v0
	v_mov_b32_e32 v15, v0
	v_mov_b32_e32 v24, v0
	v_mov_b32_e32 v25, v0
	v_mov_b32_e32 v26, v0
	v_mov_b32_e32 v27, v0
	v_mov_b32_e32 v28, v0
	v_mov_b32_e32 v29, v0
	v_mov_b32_e32 v30, v0
	v_mov_b32_e32 v31, v0
	v_mov_b32_e32 v40, v0
	v_mov_b32_e32 v41, v0
	v_mov_b32_e32 v42, v0
	v_mov_b32_e32 v43, v0
	v_mov_b32_e32 v44, v0
	v_mov_b32_e32 v45, v0
	v_mov_b32_e32 v46, v0
	v_mov_b32_e32 v47, v0
	v_mov_b32_e32 v56, v0
	v_mov_b32_e32 v57, v0
	v_mov_b32_e32 v58, v0
	v_mov_b32_e32 v59, v0
	v_mov_b32_e32 v60, v0
	v_mov_b32_e32 v61, v0
	v_mov_b32_e32 v62, v0
	v_mov_b32_e32 v63, v0
	v_mov_b32_e32 v64, v0
	v_mov_b32_e32 v65, v0
	v_mov_b32_e32 v66, v0
	v_mov_b32_e32 v67, v0
	v_mov_b32_e32 v68, v0
	v_mov_b32_e32 v69, v0
	v_mov_b32_e32 v70, v0
	v_mov_b32_e32 v71, v0
	v_mov_b32_e32 v80, v0
	v_mov_b32_e32 v81, v0
	v_mov_b32_e32 v82, v0
	v_mov_b32_e32 v83, v0
	v_mov_b32_e32 v84, v0
	v_mov_b32_e32 v85, v0
	v_mov_b32_e32 v86, v0
	v_mov_b32_e32 v87, v0
	v_mov_b32_e32 v104, v0
	v_mov_b32_e32 v105, v0
	v_mov_b32_e32 v106, v0
	v_mov_b32_e32 v107, v0
	v_mov_b32_e32 v112, v0
	v_mov_b32_e32 v113, v0
	v_mov_b32_e32 v114, v0
	v_mov_b32_e32 v115, v0
	v_mov_b32_e32 v128, v0
	v_mov_b32_e32 v129, v0
	v_mov_b32_e32 v130, v0
	v_mov_b32_e32 v131, v0
	v_mov_b32_e32 v132, v0
	v_mov_b32_e32 v133, v0
	v_mov_b32_e32 v134, v0
	v_mov_b32_e32 v135, v0
	v_mov_b32_e32 v72, v0
	v_mov_b32_e32 v73, v0
	v_mov_b32_e32 v74, v0
	v_mov_b32_e32 v75, v0
	v_mov_b32_e32 v76, v0
	v_mov_b32_e32 v77, v0
	v_mov_b32_e32 v78, v0
	v_mov_b32_e32 v79, v0
	v_mov_b32_e32 v88, v0
	v_mov_b32_e32 v89, v0
	v_mov_b32_e32 v90, v0
	v_mov_b32_e32 v91, v0
	v_mov_b32_e32 v92, v0
	v_mov_b32_e32 v93, v0
	v_mov_b32_e32 v94, v0
	v_mov_b32_e32 v95, v0
	v_mov_b32_e32 v120, v0
	v_mov_b32_e32 v121, v0
	v_mov_b32_e32 v122, v0
	v_mov_b32_e32 v123, v0
	v_mov_b32_e32 v124, v0
	v_mov_b32_e32 v125, v0
	v_mov_b32_e32 v126, v0
	v_mov_b32_e32 v127, v0
	v_mov_b32_e32 v136, v0
	v_mov_b32_e32 v137, v0
	v_mov_b32_e32 v138, v0
	v_mov_b32_e32 v139, v0
	v_mov_b32_e32 v140, v0
	v_mov_b32_e32 v141, v0
	v_mov_b32_e32 v142, v0
	v_mov_b32_e32 v143, v0
	s_nop 0
	s_nop 0

; __device__ __forceinline__ void memattn_unit(const Ctx& C, int r0, const float* kp0, const float* vp0, unsigned char* lds, int lane) {
;     const int w = C.wave, h = lane >> 4;
;     float* logits = (float*)lds;
;     const bf16_t* qmem = (const bf16_t*)(C.ws + WS_QMEM); const float* ssq = (const float*)(C.ws + ACC_SSQ);
;     {
;         unsigned q[8][8]; float rsq[8];
; #pragma unroll
;         for (int qi = 0; qi < 8; ++qi) { const u32x4 a = *(const u32x4*)(qmem + (size_t)(r0 + qi) * 1024 + lane * 16), bq = *(const u32x4*)(qmem + (size_t)(r0 + qi) * 1024 + lane * 16 + 8);
;             q[qi][0] = a.x; q[qi][1] = a.y; q[qi][2] = a.z; q[qi][3] = a.w; q[qi][4] = bq.x; q[qi][5] = bq.y; q[qi][6] = bq.z; q[qi][7] = bq.w;
;             rsq[qi] = (1.0f / sqrtf(ssq[(r0 + qi) * 4 + h] * (1.f / 256.f) + EPS)) * (0.0625f * 1.4426950408889634f); }
;         const float* kbase = kp0 + (size_t)(32 * w) * 1024 + lane * 16;
.LBB0_3144:
	s_lshl_b32 s12, s34, 3
	s_add_i32 s0, s12, 0x4000
	v_mbcnt_lo_u32_b32 v117, -1, 0
	v_mbcnt_hi_u32_b32 v117, -1, v117
	s_add_i32 s4, s12, 0x4001
	v_ashrrev_i32_e32 v66, 4, v117
	v_lshl_add_u32 v0, s0, 2, v66
	v_ashrrev_i32_e32 v1, 31, v0
	v_lshl_add_u64 v[0:1], v[0:1], 2, s[8:9]
	global_load_dword v28, v[0:1], off
	v_lshl_add_u32 v0, s4, 2, v66
	v_ashrrev_i32_e32 v1, 31, v0
	v_lshl_add_u64 v[0:1], v[0:1], 2, s[8:9]
	s_add_i32 s40, s12, 0x4002
	global_load_dword v29, v[0:1], off
	v_lshl_add_u32 v0, s40, 2, v66
	v_ashrrev_i32_e32 v1, 31, v0
	v_lshl_add_u64 v[0:1], v[0:1], 2, s[8:9]
	global_load_dword v30, v[0:1], off
	v_lshlrev_b32_e32 v64, 4, v117
	v_ashrrev_i32_e32 v65, 31, v64
	s_ashr_i32 s5, s4, 31
	s_waitcnt vmcnt(18)
	v_lshl_add_u64 v[52:53], v[64:65], 1, s[18:19]
	s_lshl_b64 s[4:5], s[4:5], 11
	s_waitcnt vmcnt(10)
	v_lshl_add_u64 v[12:13], v[52:53], 0, s[4:5]
	s_add_i32 s4, s12, 0x4003
	s_add_i32 s38, s12, 0x4004
	s_ashr_i32 s1, s0, 31
	s_ashr_i32 s5, s4, 31
	v_lshl_add_u32 v4, s4, 2, v66
	s_waitcnt vmcnt(3)
	v_lshl_add_u32 v6, s38, 2, v66
	s_lshl_b64 s[36:37], s[0:1], 11
	s_lshl_b64 s[0:1], s[4:5], 11
	v_ashrrev_i32_e32 v5, 31, v4
	v_ashrrev_i32_e32 v7, 31, v6
	v_lshl_add_u64 v[8:9], v[52:53], 0, s[36:37]
	v_lshl_add_u64 v[20:21], v[52:53], 0, s[0:1]
	global_load_dwordx4 v[0:3], v[12:13], off offset:16
	v_lshl_add_u64 v[24:25], v[4:5], 2, s[8:9]
	v_lshl_add_u64 v[26:27], v[6:7], 2, s[8:9]
	global_load_dwordx4 v[4:7], v[8:9], off
	s_nop 0
	global_load_dwordx4 v[8:11], v[8:9], off offset:16
	s_nop 0
	global_load_dwordx4 v[12:15], v[12:13], off
	s_nop 0
	global_load_dwordx4 v[16:19], v[20:21], off
	s_nop 0
	global_load_dwordx4 v[20:23], v[20:21], off offset:16
	s_nop 0
	global_load_dword v32, v[24:25], off
	s_ashr_i32 s41, s40, 31
	s_ashr_i32 s39, s38, 31
	v_lshl_add_u32 v126, v66, 10, s3
	v_lshl_add_u64 v[112:113], v[64:65], 2, s[22:23]
	s_waitcnt vmcnt(9)
	v_fmamk_f32 v24, v28, 0x3b800000, v114
	v_cmp_gt_f32_e32 vcc, s47, v24
	s_waitcnt vmcnt(8)
	v_fmamk_f32 v25, v29, 0x3b800000, v114
	v_mul_f32_e32 v29, 0x4f800000, v24
	v_cndmask_b32_e32 v24, v24, v29, vcc
	v_cmp_gt_f32_e64 s[0:1], s47, v25
	s_waitcnt vmcnt(7)
	v_fmamk_f32 v28, v30, 0x3b800000, v114
	v_mul_f32_e32 v30, 0x4f800000, v25
	v_cndmask_b32_e64 v25, v25, v30, s[0:1]
	v_sqrt_f32_e32 v29, v24
	v_sqrt_f32_e32 v30, v25
	v_mul_f32_e32 v31, 0x4f800000, v28
	v_cmp_gt_f32_e64 s[4:5], s47, v28
	v_add_u32_e32 v33, -1, v29
	v_add_u32_e32 v35, -1, v30
	v_fma_f32 v37, -v33, v29, v24
	v_add_u32_e32 v34, 1, v29
	v_fma_f32 v39, -v35, v30, v25
	v_cmp_ge_f32_e64 s[6:7], 0, v37
	v_add_u32_e32 v36, 1, v30
	v_fma_f32 v38, -v34, v29, v24
	v_cndmask_b32_e64 v29, v29, v33, s[6:7]
	v_cmp_ge_f32_e64 s[6:7], 0, v39
	v_fma_f32 v40, -v36, v30, v25
	v_cndmask_b32_e64 v28, v28, v31, s[4:5]
	v_cndmask_b32_e64 v30, v30, v35, s[6:7]
	v_cmp_lt_f32_e64 s[6:7], 0, v38
	v_sqrt_f32_e32 v31, v28
	s_waitcnt vmcnt(0)
	v_fmamk_f32 v32, v32, 0x3b800000, v114
	v_cndmask_b32_e64 v29, v29, v34, s[6:7]
	v_cmp_lt_f32_e64 s[6:7], 0, v40
	v_mul_f32_e32 v33, 0x37800000, v29
	v_cndmask_b32_e32 v29, v29, v33, vcc
	v_cndmask_b32_e64 v30, v30, v36, s[6:7]
	v_mul_f32_e32 v34, 0x37800000, v30
	v_cmp_class_f32_e32 vcc, v24, v115
	v_cndmask_b32_e64 v30, v30, v34, s[0:1]
	s_nop 0
	v_cndmask_b32_e32 v24, v29, v24, vcc
	v_cmp_class_f32_e32 vcc, v25, v115
	v_div_scale_f32 v29, s[0:1], v24, v24, 1.0
	s_nop 0
	v_cndmask_b32_e32 v25, v30, v25, vcc
	v_div_scale_f32 v33, s[0:1], v25, v25, 1.0
	v_rcp_f32_e32 v35, v33
	v_div_scale_f32 v36, s[0:1], 1.0, v25, 1.0
	v_rcp_f32_e32 v34, v29
	v_fma_f32 v38, -v33, v35, 1.0
	v_fmac_f32_e32 v35, v38, v35
	v_mul_f32_e32 v38, v36, v35
	v_fma_f32 v40, -v33, v38, v36
	v_fmac_f32_e32 v38, v40, v35
	global_load_dword v40, v[26:27], off
	v_fma_f32 v37, -v29, v34, 1.0
	v_div_scale_f32 v30, vcc, 1.0, v24, 1.0
	v_fmac_f32_e32 v34, v37, v34
	v_mul_f32_e32 v37, v30, v34
	v_fma_f32 v39, -v29, v37, v30
	v_fmac_f32_e32 v37, v39, v34
	v_fma_f32 v29, -v29, v37, v30
	v_fma_f32 v30, -v33, v38, v36
	v_div_fmas_f32 v29, v29, v34, v37
	s_mov_b64 vcc, s[0:1]
	v_div_fixup_f32 v24, v29, v24, 1.0
	v_div_fmas_f32 v29, v30, v35, v38
	v_mul_f32_e32 v118, 0x3db8aa3b, v24
	v_div_fixup_f32 v24, v29, v25, 1.0
	v_mul_f32_e32 v119, 0x3db8aa3b, v24
	v_add_u32_e32 v24, -1, v31
	v_fma_f32 v25, -v24, v31, v28
	v_cmp_ge_f32_e32 vcc, 0, v25
	v_add_u32_e32 v25, 1, v31
	v_fma_f32 v26, -v25, v31, v28
	v_cndmask_b32_e32 v24, v31, v24, vcc
	v_cmp_lt_f32_e32 vcc, 0, v26
	s_lshl_b64 s[0:1], s[40:41], 11
	s_waitcnt vmcnt(0)
; __device__ __forceinline__ void memattn_unit(const Ctx& C, int r0, const float* kp0, const float* vp0, unsigned char* lds, int lane) {
;     ...
;         unsigned q[8][8]; float rsq[8];
; #pragma unroll
;         for (int qi = 0; qi < 8; ++qi) { const u32x4 a = *(const u32x4*)(qmem + (size_t)(r0 + qi) * 1024 + lane * 16), bq = *(const u32x4*)(qmem + (size_t)(r0 + qi) * 1024 + lane * 16 + 8);
;             q[qi][0] = a.x; q[qi][1] = a.y; q[qi][2] = a.z; q[qi][3] = a.w; q[qi][4] = bq.x; q[qi][5] = bq.y; q[qi][6] = bq.z; q[qi][7] = bq.w;
;             rsq[qi] = (1.0f / sqrtf(ssq[(r0 + qi) * 4 + h] * (1.f / 256.f) + EPS)) * (0.0625f * 1.4426950408889634f); }
	v_fmamk_f32 v40, v40, 0x3b800000, v114
	v_cndmask_b32_e32 v24, v24, v25, vcc
	v_mul_f32_e32 v25, 0x37800000, v24
	v_cndmask_b32_e64 v24, v24, v25, s[4:5]
	v_cmp_class_f32_e32 vcc, v28, v115
	s_nop 1
	v_cndmask_b32_e32 v41, v24, v28, vcc
	v_div_scale_f32 v42, s[4:5], v41, v41, 1.0
	v_rcp_f32_e32 v43, v42
	s_add_i32 s4, s12, 0x4005
	v_lshl_add_u64 v[28:29], v[52:53], 0, s[0:1]
	v_cmp_gt_f32_e64 s[0:1], s47, v32
	v_fma_f32 v33, -v42, v43, 1.0
	v_fmac_f32_e32 v43, v33, v43
	v_mul_f32_e32 v33, 0x4f800000, v32
	s_ashr_i32 s5, s4, 31
	v_cndmask_b32_e64 v46, v32, v33, s[0:1]
	s_lshl_b64 s[6:7], s[4:5], 11
	v_lshl_add_u32 v32, s4, 2, v66
	v_lshl_add_u64 v[36:37], v[52:53], 0, s[6:7]
	v_ashrrev_i32_e32 v33, 31, v32
	global_load_dwordx4 v[24:27], v[28:29], off
	s_nop 0
	global_load_dwordx4 v[28:31], v[28:29], off offset:16
	v_lshl_add_u64 v[38:39], v[32:33], 2, s[8:9]
	global_load_dwordx4 v[32:35], v[36:37], off offset:16
	global_load_dword v54, v[38:39], off
	v_sqrt_f32_e32 v47, v46
	v_div_scale_f32 v44, vcc, 1.0, v41, 1.0
	v_mul_f32_e32 v45, v44, v43
	v_fma_f32 v38, -v42, v45, v44
	v_fmac_f32_e32 v45, v38, v43
	v_add_u32_e32 v39, -1, v47
	v_fma_f32 v38, -v42, v45, v44
	v_fma_f32 v42, -v39, v47, v46
	v_cmp_ge_f32_e64 s[4:5], 0, v42
	v_add_u32_e32 v42, 1, v47
	v_fma_f32 v44, -v42, v47, v46
	v_cndmask_b32_e64 v39, v47, v39, s[4:5]
	v_cmp_lt_f32_e64 s[4:5], 0, v44
	v_div_fmas_f32 v38, v38, v43, v45
	v_div_fixup_f32 v38, v38, v41, 1.0
	v_cndmask_b32_e64 v39, v39, v42, s[4:5]
	v_mul_f32_e32 v42, 0x37800000, v39
	v_cndmask_b32_e64 v39, v39, v42, s[0:1]
	v_cmp_class_f32_e64 s[0:1], v46, v115
	v_mul_f32_e32 v120, 0x3db8aa3b, v38
	s_add_i32 s6, s12, 0x4006
	v_cndmask_b32_e64 v39, v39, v46, s[0:1]
	v_div_scale_f32 v42, s[0:1], v39, v39, 1.0
	v_rcp_f32_e32 v44, v42
	s_lshl_b64 s[4:5], s[38:39], 11
	v_lshl_add_u64 v[48:49], v[52:53], 0, s[4:5]
	s_ashr_i32 s7, s6, 31
	v_fma_f32 v38, -v42, v44, 1.0
	v_fmac_f32_e32 v44, v38, v44
	v_div_scale_f32 v38, vcc, 1.0, v39, 1.0
	v_mul_f32_e32 v41, v38, v44
	v_fma_f32 v43, -v42, v41, v38
	v_fmac_f32_e32 v41, v43, v44
	v_fma_f32 v38, -v42, v41, v38
	v_div_fmas_f32 v38, v38, v44, v41
	v_div_fixup_f32 v41, v38, v39, 1.0
	v_lshl_add_u32 v38, s6, 2, v66
	v_ashrrev_i32_e32 v39, 31, v38
	v_mul_f32_e32 v42, 0x4f800000, v40
	v_cmp_gt_f32_e32 vcc, s47, v40
	v_lshl_add_u64 v[38:39], v[38:39], 2, s[8:9]
	global_load_dword v67, v[38:39], off
	s_nop 0
	global_load_dwordx4 v[36:39], v[36:37], off
	v_cndmask_b32_e32 v40, v40, v42, vcc
	v_sqrt_f32_e32 v42, v40
	v_mul_f32_e32 v121, 0x3db8aa3b, v41
	v_add_u32_e32 v41, -1, v42
	v_fma_f32 v43, -v41, v42, v40
	v_cmp_ge_f32_e64 s[0:1], 0, v43
	v_add_u32_e32 v43, 1, v42
	s_waitcnt vmcnt(2)
	v_fmamk_f32 v54, v54, 0x3b800000, v114
	v_cndmask_b32_e64 v41, v42, v41, s[0:1]
	v_fma_f32 v42, -v43, v42, v40
	v_cmp_lt_f32_e64 s[0:1], 0, v42
	v_mul_f32_e32 v62, 0x4f800000, v54
	s_waitcnt vmcnt(1)
	v_fmamk_f32 v67, v67, 0x3b800000, v114
	v_cndmask_b32_e64 v41, v41, v43, s[0:1]
	v_mul_f32_e32 v42, 0x37800000, v41
	v_cndmask_b32_e32 v41, v41, v42, vcc
	v_cmp_class_f32_e32 vcc, v40, v115
	v_mul_f32_e32 v74, 0x4f800000, v67
	s_nop 0
	v_cndmask_b32_e32 v55, v41, v40, vcc
	v_div_scale_f32 v56, s[0:1], v55, v55, 1.0
	s_add_i32 s0, s12, 0x4007
	s_ashr_i32 s1, s0, 31
	s_lshl_b64 s[38:39], s[0:1], 11
	v_lshl_add_u32 v40, s0, 2, v66
	v_lshl_add_u64 v[60:61], v[52:53], 0, s[38:39]
	v_ashrrev_i32_e32 v41, 31, v40
	v_lshl_add_u64 v[44:45], v[40:41], 2, s[8:9]
	global_load_dwordx4 v[40:43], v[60:61], off offset:16
	global_load_dword v68, v[44:45], off
	v_rcp_f32_e32 v57, v56
	v_cmp_gt_f32_e64 s[0:1], s47, v54
	global_load_dwordx4 v[44:47], v[48:49], off
	s_nop 0
	global_load_dwordx4 v[48:51], v[48:49], off offset:16
	v_cndmask_b32_e64 v54, v54, v62, s[0:1]
	v_fma_f32 v58, -v56, v57, 1.0
	v_fmac_f32_e32 v57, v58, v57
	v_div_scale_f32 v58, vcc, 1.0, v55, 1.0
	v_sqrt_f32_e32 v62, v54
	v_mul_f32_e32 v59, v58, v57
	v_fma_f32 v63, -v56, v59, v58
	v_fmac_f32_e32 v59, v63, v57
	v_fma_f32 v56, -v56, v59, v58
	v_add_u32_e32 v58, -1, v62
	v_fma_f32 v63, -v58, v62, v54
	v_cmp_ge_f32_e64 s[4:5], 0, v63
	v_add_u32_e32 v63, 1, v62
	s_waitcnt vmcnt(2)
; __device__ __forceinline__ void memattn_unit(const Ctx& C, int r0, const float* kp0, const float* vp0, unsigned char* lds, int lane) {
;     ...
;         unsigned q[8][8]; float rsq[8];
; #pragma unroll
;         for (int qi = 0; qi < 8; ++qi) { const u32x4 a = *(const u32x4*)(qmem + (size_t)(r0 + qi) * 1024 + lane * 16), bq = *(const u32x4*)(qmem + (size_t)(r0 + qi) * 1024 + lane * 16 + 8);
;             q[qi][0] = a.x; q[qi][1] = a.y; q[qi][2] = a.z; q[qi][3] = a.w; q[qi][4] = bq.x; q[qi][5] = bq.y; q[qi][6] = bq.z; q[qi][7] = bq.w;
;             rsq[qi] = (1.0f / sqrtf(ssq[(r0 + qi) * 4 + h] * (1.f / 256.f) + EPS)) * (0.0625f * 1.4426950408889634f); }
;         const float* kbase = kp0 + (size_t)(32 * w) * 1024 + lane * 16;
; #pragma unroll 1
;         for (int mb = 0; mb < 8; ++mb) {
;             f32x4 kr[4][4];
; #pragma unroll
;             for (int u = 0; u < 4; ++u)
; #pragma unroll
;                 for (int j = 0; j < 4; ++j) kr[u][j] = *(const f32x4*)(kbase + (size_t)(mb * 4 + u) * 1024 + 4 * j);
	v_fmamk_f32 v68, v68, 0x3b800000, v114
	v_cndmask_b32_e64 v58, v62, v58, s[4:5]
	v_fma_f32 v62, -v63, v62, v54
	v_cmp_lt_f32_e64 s[4:5], 0, v62
	s_nop 1
	v_cndmask_b32_e64 v58, v58, v63, s[4:5]
	v_mul_f32_e32 v62, 0x37800000, v58
	v_cndmask_b32_e64 v58, v58, v62, s[0:1]
	v_cmp_class_f32_e64 s[0:1], v54, v115
	s_nop 1
	v_cndmask_b32_e64 v69, v58, v54, s[0:1]
	v_div_scale_f32 v70, s[0:1], v69, v69, 1.0
	v_rcp_f32_e32 v71, v70
	v_div_fmas_f32 v54, v56, v57, v59
	v_div_fixup_f32 v54, v54, v55, 1.0
	s_lshl_b64 s[0:1], s[6:7], 11
	v_mul_f32_e32 v122, 0x3db8aa3b, v54
	v_fma_f32 v54, -v70, v71, 1.0
	v_lshl_add_u64 v[56:57], v[52:53], 0, s[0:1]
	v_fmac_f32_e32 v71, v54, v71
	global_load_dwordx4 v[52:55], v[56:57], off
	s_nop 0
	global_load_dwordx4 v[56:59], v[56:57], off offset:16
	s_nop 0
	global_load_dwordx4 v[60:63], v[60:61], off
	v_cmp_gt_f32_e64 s[0:1], s47, v67
	v_div_scale_f32 v72, vcc, 1.0, v69, 1.0
	s_nop 0
	v_cndmask_b32_e64 v67, v67, v74, s[0:1]
	v_sqrt_f32_e32 v74, v67
	v_mul_f32_e32 v73, v72, v71
	v_fma_f32 v75, -v70, v73, v72
	v_fmac_f32_e32 v73, v75, v71
	v_fma_f32 v70, -v70, v73, v72
	v_add_u32_e32 v72, -1, v74
	v_fma_f32 v75, -v72, v74, v67
	v_cmp_ge_f32_e64 s[4:5], 0, v75
	v_add_u32_e32 v75, 1, v74
	v_div_fmas_f32 v70, v70, v71, v73
	v_cndmask_b32_e64 v72, v74, v72, s[4:5]
	v_fma_f32 v74, -v75, v74, v67
	v_cmp_lt_f32_e64 s[4:5], 0, v74
	v_div_fixup_f32 v69, v70, v69, 1.0
	v_mul_f32_e32 v71, 0x4f800000, v68
	v_cndmask_b32_e64 v72, v72, v75, s[4:5]
	v_mul_f32_e32 v74, 0x37800000, v72
	v_cndmask_b32_e64 v72, v72, v74, s[0:1]
	v_cmp_class_f32_e64 s[0:1], v67, v115
	v_mul_f32_e32 v123, 0x3db8aa3b, v69
	s_nop 0
	v_cndmask_b32_e64 v67, v72, v67, s[0:1]
	v_div_scale_f32 v72, s[0:1], v67, v67, 1.0
	v_rcp_f32_e32 v74, v72
	v_cmp_gt_f32_e64 s[0:1], s47, v68
	v_fma_f32 v69, -v72, v74, 1.0
	s_nop 0
	v_cndmask_b32_e64 v68, v68, v71, s[0:1]
	v_fmac_f32_e32 v74, v69, v74
	v_div_scale_f32 v69, vcc, 1.0, v67, 1.0
	v_sqrt_f32_e32 v71, v68
	v_mul_f32_e32 v70, v69, v74
	v_fma_f32 v73, -v72, v70, v69
	v_fmac_f32_e32 v70, v73, v74
	v_fma_f32 v69, -v72, v70, v69
	v_add_u32_e32 v72, -1, v71
	v_fma_f32 v73, -v72, v71, v68
	v_cmp_ge_f32_e64 s[4:5], 0, v73
	v_add_u32_e32 v73, 1, v71
	v_div_fmas_f32 v69, v69, v74, v70
	v_cndmask_b32_e64 v72, v71, v72, s[4:5]
	v_fma_f32 v71, -v73, v71, v68
	v_cmp_lt_f32_e64 s[4:5], 0, v71
	v_div_fixup_f32 v67, v69, v67, 1.0
	v_mul_f32_e32 v124, 0x3db8aa3b, v67
	v_cndmask_b32_e64 v71, v72, v73, s[4:5]
	v_mul_f32_e32 v72, 0x37800000, v71
	v_cndmask_b32_e64 v71, v71, v72, s[0:1]
	v_cmp_class_f32_e64 s[0:1], v68, v115
	s_mov_b64 s[4:5], 0
	s_nop 0
	v_cndmask_b32_e64 v68, v71, v68, s[0:1]
	v_div_scale_f32 v71, s[0:1], v68, v68, 1.0
	v_rcp_f32_e32 v72, v71
	s_nop 0
	v_fma_f32 v67, -v71, v72, 1.0
	v_fmac_f32_e32 v72, v67, v72
	v_div_scale_f32 v67, vcc, 1.0, v68, 1.0
	v_mul_f32_e32 v69, v67, v72
	v_fma_f32 v70, -v71, v69, v67
	v_fmac_f32_e32 v69, v70, v72
	v_fma_f32 v67, -v71, v69, v67
	v_div_fmas_f32 v67, v67, v72, v69
	v_div_fixup_f32 v67, v67, v68, 1.0
	v_mul_f32_e32 v125, 0x3db8aa3b, v67
	v_and_b32_e32 v67, 15, v117
	v_cmp_eq_u32_e32 vcc, 0, v67
	v_lshl_add_u64 v[236:237], v[112:113], 0, s[4:5]
	v_lshl_add_u64 v[238:239], v[236:237], 0, s[26:27]
	v_lshl_add_u64 v[240:241], v[236:237], 0, s[28:29]
	v_lshl_add_u64 v[242:243], v[236:237], 0, s[30:31]
	global_load_dwordx4 v[148:151], v[236:237], off
	global_load_dwordx4 v[152:155], v[236:237], off offset:16
	global_load_dwordx4 v[156:159], v[236:237], off offset:32
	global_load_dwordx4 v[160:163], v[236:237], off offset:48
	global_load_dwordx4 v[164:167], v[238:239], off
	global_load_dwordx4 v[168:171], v[238:239], off offset:16
	global_load_dwordx4 v[172:175], v[238:239], off offset:32
	global_load_dwordx4 v[176:179], v[238:239], off offset:48
	global_load_dwordx4 v[180:183], v[240:241], off
	global_load_dwordx4 v[184:187], v[240:241], off offset:16
	global_load_dwordx4 v[188:191], v[240:241], off offset:32
	global_load_dwordx4 v[192:195], v[240:241], off offset:48
	global_load_dwordx4 v[196:199], v[242:243], off
	global_load_dwordx4 v[200:203], v[242:243], off offset:16
	global_load_dwordx4 v[204:207], v[242:243], off offset:32
	global_load_dwordx4 v[208:211], v[242:243], off offset:48
	s_nop 0

;   __device__ __forceinline__ bool next(int i,AttnUnit&u)const{ if(i>=2)return false; const int s=vcu&15; u.bh=vcu>>4; u.qb=(i==0)?s:31-s; return true; }
;     __device__ __forceinline__ bool next(int i, attn_body::AttnUnit& u) const { if (i >= n) return false; const int s = v & 15; u.bh = v >> 4; u.qb = (i0 + i == 0) ? s : 31 - s; return true; }
; template <class Epi, class Sched, bool ALIGN_EPI = false, bool SP2 = false>
; __device__ __forceinline__ void gemm_phase(PG8_LAS unsigned char* lds, const Gemm g, const Sched& S, const Epi& E) {
;     ...
;         const bool has_next = S.next(ui + 1, nxt);
;         const char* nA = has_next ? (const char*)g.A + (size_t)nxt.pm * tstep : cA; const char* nB = has_next ? (const char*)g.Bt + (size_t)nxt.pn * tstep : cB;
;         for (int t = 0; t < nt; t += 2) {
;             const bool last = (t == nt - 2);
;             const char* a1 = cA + (size_t)(t + 1) * kstep;
;             const char* a2 = last ? nA : cA + (size_t)(t + 2) * kstep; const char* b2 = last ? nB : cB + (size_t)(t + 2) * kstep;
;             const char* a3 = a2 + kstep; const char* b3 = b2 + kstep;
;             if (last && has_next) S.a_ready(nxt);
;     ...
;         for (int a = 0; a < 2; ++a)
; #pragma unroll
;             for (int b = 0; b < 2; ++b)
; #pragma unroll
;                 for (int m = 0; m < 4; ++m)
; #pragma unroll
;                     for (int n = 0; n < 2; ++n) acc[a][b][m][n] = (f32x4){0.f, 0.f, 0.f, 0.f};
;         cur = nxt; cA = nA; cB = nB; ++ui;
.LBB0_3232:
	s_ashr_i32 s23, s22, 31
	s_lshl_b64 s[24:25], s[22:23], 19
	s_add_u32 s24, s33, s24
	s_addc_u32 s25, s40, s25
	s_and_b64 s[26:27], s[4:5], exec
	s_cselect_b32 s23, s25, s35
	s_cselect_b32 s29, s24, s34
	s_ashr_i32 s21, s20, 31
	s_lshl_b64 s[26:27], s[20:21], 19
	s_add_u32 s26, s41, s26
	s_addc_u32 s27, s42, s27
	s_and_b64 s[38:39], s[4:5], exec
	s_cselect_b32 s21, s27, s37
	s_cselect_b32 s56, s26, s36
	s_add_u32 s34, s34, 0x40080
	s_addc_u32 s35, s35, 0
	s_add_u32 s57, s36, 0x100
	v_mov_b32_e32 v0, 0
	s_addc_u32 s58, s37, 0
	s_mov_b32 s59, -2
	s_waitcnt lgkmcnt(0)
	v_mov_b32_e32 v1, v0
	v_mov_b32_e32 v2, v0
	v_mov_b32_e32 v3, v0
	v_mov_b32_e32 v4, v0
	v_mov_b32_e32 v5, v0
	v_mov_b32_e32 v6, v0
	v_mov_b32_e32 v7, v0
	v_mov_b32_e32 v16, v0
	v_mov_b32_e32 v17, v0
	v_mov_b32_e32 v18, v0
	v_mov_b32_e32 v19, v0
	v_mov_b32_e32 v20, v0
	v_mov_b32_e32 v21, v0
	v_mov_b32_e32 v22, v0
	v_mov_b32_e32 v23, v0
	v_mov_b32_e32 v32, v0
	v_mov_b32_e32 v33, v0
	v_mov_b32_e32 v34, v0
	v_mov_b32_e32 v35, v0
	v_mov_b32_e32 v36, v0
	v_mov_b32_e32 v37, v0
	v_mov_b32_e32 v38, v0
	v_mov_b32_e32 v39, v0
	v_mov_b32_e32 v48, v0
	v_mov_b32_e32 v49, v0
	v_mov_b32_e32 v50, v0
	v_mov_b32_e32 v51, v0
	v_mov_b32_e32 v52, v0
	v_mov_b32_e32 v53, v0
	v_mov_b32_e32 v54, v0
	v_mov_b32_e32 v55, v0
	v_mov_b32_e32 v8, v0
	v_mov_b32_e32 v9, v0
	v_mov_b32_e32 v10, v0
	v_mov_b32_e32 v11, v0
	v_mov_b32_e32 v12, v0
	v_mov_b32_e32 v13, v0
	v_mov_b32_e32 v14, v0
	v_mov_b32_e32 v15, v0
	v_mov_b32_e32 v24, v0
	v_mov_b32_e32 v25, v0
	v_mov_b32_e32 v26, v0
	v_mov_b32_e32 v27, v0
	v_mov_b32_e32 v28, v0
	v_mov_b32_e32 v29, v0
	v_mov_b32_e32 v30, v0
	v_mov_b32_e32 v31, v0
	v_mov_b32_e32 v40, v0
	v_mov_b32_e32 v41, v0
	v_mov_b32_e32 v42, v0
	v_mov_b32_e32 v43, v0
	v_mov_b32_e32 v44, v0
	v_mov_b32_e32 v45, v0
	v_mov_b32_e32 v46, v0
	v_mov_b32_e32 v47, v0
	v_mov_b32_e32 v56, v0
	v_mov_b32_e32 v57, v0
	v_mov_b32_e32 v58, v0
	v_mov_b32_e32 v59, v0
	v_mov_b32_e32 v60, v0
	v_mov_b32_e32 v61, v0
	v_mov_b32_e32 v62, v0
	v_mov_b32_e32 v63, v0
	v_mov_b32_e32 v64, v0
	v_mov_b32_e32 v65, v0
	v_mov_b32_e32 v66, v0
	v_mov_b32_e32 v67, v0
	v_mov_b32_e32 v68, v0
	v_mov_b32_e32 v69, v0
	v_mov_b32_e32 v70, v0
	v_mov_b32_e32 v71, v0
	v_mov_b32_e32 v80, v0
	v_mov_b32_e32 v81, v0
	v_mov_b32_e32 v82, v0
	v_mov_b32_e32 v83, v0
	v_mov_b32_e32 v84, v0
	v_mov_b32_e32 v85, v0
	v_mov_b32_e32 v86, v0
	v_mov_b32_e32 v87, v0
	v_mov_b32_e32 v96, v0
	v_mov_b32_e32 v97, v0
	v_mov_b32_e32 v98, v0
	v_mov_b32_e32 v99, v0
	v_mov_b32_e32 v100, v0
	v_mov_b32_e32 v101, v0
	v_mov_b32_e32 v102, v0
	v_mov_b32_e32 v103, v0
	v_mov_b32_e32 v112, v0
	v_mov_b32_e32 v113, v0
	v_mov_b32_e32 v114, v0
	v_mov_b32_e32 v115, v0
	v_mov_b32_e32 v116, v0
	v_mov_b32_e32 v117, v0
	v_mov_b32_e32 v118, v0
	v_mov_b32_e32 v119, v0
	v_mov_b32_e32 v72, v0
	v_mov_b32_e32 v73, v0
	v_mov_b32_e32 v74, v0
	v_mov_b32_e32 v75, v0
	v_mov_b32_e32 v76, v0
	v_mov_b32_e32 v77, v0
	v_mov_b32_e32 v78, v0
	v_mov_b32_e32 v79, v0
	v_mov_b32_e32 v88, v0
	v_mov_b32_e32 v89, v0
	v_mov_b32_e32 v90, v0
	v_mov_b32_e32 v91, v0
	v_mov_b32_e32 v92, v0
	v_mov_b32_e32 v93, v0
	v_mov_b32_e32 v94, v0
	v_mov_b32_e32 v95, v0
	v_mov_b32_e32 v104, v0
	v_mov_b32_e32 v105, v0
	v_mov_b32_e32 v106, v0
	v_mov_b32_e32 v107, v0
	v_mov_b32_e32 v108, v0
	v_mov_b32_e32 v109, v0
	v_mov_b32_e32 v110, v0
	v_mov_b32_e32 v111, v0
	v_mov_b32_e32 v120, v0
	v_mov_b32_e32 v121, v0
	v_mov_b32_e32 v122, v0
	v_mov_b32_e32 v123, v0
	v_mov_b32_e32 v124, v0
	v_mov_b32_e32 v125, v0
	v_mov_b32_e32 v126, v0
	v_mov_b32_e32 v127, v0
	s_nop 0
	s_nop 0
	s_nop 0
	s_nop 0
	s_nop 0
	s_nop 0
	s_nop 0
	s_nop 0
	s_nop 0
	s_nop 0
	s_nop 0

;   __device__ __forceinline__ bool next(int i,AttnUnit&u)const{ if(i>=2)return false; const int s=vcu&15; u.bh=vcu>>4; u.qb=(i==0)?s:31-s; return true; }
;     __device__ __forceinline__ bool next(int i, attn_body::AttnUnit& u) const { if (i >= n) return false; const int s = v & 15; u.bh = v >> 4; u.qb = (i0 + i == 0) ? s : 31 - s; return true; }
; template <class Epi, class Sched, bool ALIGN_EPI = false, bool SP2 = false>
; __device__ __forceinline__ void gemm_phase(PG8_LAS unsigned char* lds, const Gemm g, const Sched& S, const Epi& E) {
;     ...
;         const bool has_next = S.next(ui + 1, nxt);
;         const char* nA = has_next ? (const char*)g.A + (size_t)nxt.pm * tstep : cA; const char* nB = has_next ? (const char*)g.Bt + (size_t)nxt.pn * tstep : cB;
;         for (int t = 0; t < nt; t += 2) {
;             const bool last = (t == nt - 2);
;             const char* a1 = cA + (size_t)(t + 1) * kstep;
;             const char* a2 = last ? nA : cA + (size_t)(t + 2) * kstep; const char* b2 = last ? nB : cB + (size_t)(t + 2) * kstep;
;             const char* a3 = a2 + kstep; const char* b3 = b2 + kstep;
;             if (last && has_next) S.a_ready(nxt);
;     ...
;         for (int a = 0; a < 2; ++a)
; #pragma unroll
;             for (int b = 0; b < 2; ++b)
; #pragma unroll
;                 for (int m = 0; m < 4; ++m)
; #pragma unroll
;                     for (int n = 0; n < 2; ++n) acc[a][b][m][n] = (f32x4){0.f, 0.f, 0.f, 0.f};
;         cur = nxt; cA = nA; cB = nB; ++ui;
.LBB0_3385:
	s_ashr_i32 s51, s50, 31
	s_lshl_b64 s[52:53], s[50:51], 19
	s_add_u32 s52, s2, s52
	s_addc_u32 s53, s3, s53
	s_and_b64 s[54:55], s[8:9], exec
	s_cselect_b32 s11, s53, s35
	s_cselect_b32 s13, s52, s34
	s_ashr_i32 s47, s46, 31
	s_lshl_b64 s[54:55], s[46:47], 19
	s_add_u32 s54, s33, s54
	s_addc_u32 s55, s62, s55
	s_and_b64 s[58:59], s[8:9], exec
	s_cselect_b32 s47, s55, s57
	s_cselect_b32 s51, s54, s56
	s_add_u32 s34, s34, 0x40080
	s_addc_u32 s35, s35, 0
	s_add_u32 s60, s56, 0x100
	v_mov_b32_e32 v0, 0
	s_addc_u32 s61, s57, 0
	s_mov_b32 s79, -2
	v_mov_b32_e32 v1, v0
	v_mov_b32_e32 v2, v0
	v_mov_b32_e32 v3, v0
	v_mov_b32_e32 v4, v0
	v_mov_b32_e32 v5, v0
	v_mov_b32_e32 v6, v0
	v_mov_b32_e32 v7, v0
	v_mov_b32_e32 v16, v0
	v_mov_b32_e32 v17, v0
	v_mov_b32_e32 v18, v0
	v_mov_b32_e32 v19, v0
	v_mov_b32_e32 v20, v0
	v_mov_b32_e32 v21, v0
	v_mov_b32_e32 v22, v0
	v_mov_b32_e32 v23, v0
	v_mov_b32_e32 v56, v0
	v_mov_b32_e32 v57, v0
	v_mov_b32_e32 v58, v0
	v_mov_b32_e32 v59, v0
	v_mov_b32_e32 v60, v0
	v_mov_b32_e32 v61, v0
	v_mov_b32_e32 v62, v0
	v_mov_b32_e32 v63, v0
	v_mov_b32_e32 v72, v0
	v_mov_b32_e32 v73, v0
	v_mov_b32_e32 v74, v0
	v_mov_b32_e32 v75, v0
	v_mov_b32_e32 v76, v0
	v_mov_b32_e32 v77, v0
	v_mov_b32_e32 v78, v0
	v_mov_b32_e32 v79, v0
	v_mov_b32_e32 v8, v0
	v_mov_b32_e32 v9, v0
	v_mov_b32_e32 v10, v0
	v_mov_b32_e32 v11, v0
	v_mov_b32_e32 v12, v0
	v_mov_b32_e32 v13, v0
	v_mov_b32_e32 v14, v0
	v_mov_b32_e32 v15, v0
	v_mov_b32_e32 v40, v0
	v_mov_b32_e32 v41, v0
	v_mov_b32_e32 v42, v0
	v_mov_b32_e32 v43, v0
	v_mov_b32_e32 v44, v0
	v_mov_b32_e32 v45, v0
	v_mov_b32_e32 v46, v0
	v_mov_b32_e32 v47, v0
	v_mov_b32_e32 v64, v0
	v_mov_b32_e32 v65, v0
	v_mov_b32_e32 v66, v0
	v_mov_b32_e32 v67, v0
	v_mov_b32_e32 v68, v0
	v_mov_b32_e32 v69, v0
	v_mov_b32_e32 v70, v0
	v_mov_b32_e32 v71, v0
	v_mov_b32_e32 v80, v0
	v_mov_b32_e32 v81, v0
	v_mov_b32_e32 v82, v0
	v_mov_b32_e32 v83, v0
	v_mov_b32_e32 v84, v0
	v_mov_b32_e32 v85, v0
	v_mov_b32_e32 v86, v0
	v_mov_b32_e32 v87, v0
	v_mov_b32_e32 v88, v0
	v_mov_b32_e32 v89, v0
	v_mov_b32_e32 v90, v0
	v_mov_b32_e32 v91, v0
	v_mov_b32_e32 v92, v0
	v_mov_b32_e32 v93, v0
	v_mov_b32_e32 v94, v0
	v_mov_b32_e32 v95, v0
	v_mov_b32_e32 v104, v0
	v_mov_b32_e32 v105, v0
	v_mov_b32_e32 v106, v0
	v_mov_b32_e32 v107, v0
	v_mov_b32_e32 v108, v0
	v_mov_b32_e32 v109, v0
	v_mov_b32_e32 v110, v0
	v_mov_b32_e32 v111, v0
	v_mov_b32_e32 v120, v0
	v_mov_b32_e32 v121, v0
	v_mov_b32_e32 v122, v0
	v_mov_b32_e32 v123, v0
	v_mov_b32_e32 v124, v0
	v_mov_b32_e32 v125, v0
	v_mov_b32_e32 v126, v0
	v_mov_b32_e32 v127, v0
	v_mov_b32_e32 v136, v0
	v_mov_b32_e32 v137, v0
	v_mov_b32_e32 v138, v0
	v_mov_b32_e32 v139, v0
	v_mov_b32_e32 v140, v0
	v_mov_b32_e32 v141, v0
	v_mov_b32_e32 v142, v0
	v_mov_b32_e32 v143, v0
	v_mov_b32_e32 v96, v0
	v_mov_b32_e32 v97, v0
	v_mov_b32_e32 v98, v0
	v_mov_b32_e32 v99, v0
	v_mov_b32_e32 v100, v0
	v_mov_b32_e32 v101, v0
	v_mov_b32_e32 v102, v0
	v_mov_b32_e32 v103, v0
	v_mov_b32_e32 v112, v0
	v_mov_b32_e32 v113, v0
	v_mov_b32_e32 v114, v0
	v_mov_b32_e32 v115, v0
	v_mov_b32_e32 v116, v0
	v_mov_b32_e32 v117, v0
	v_mov_b32_e32 v118, v0
	v_mov_b32_e32 v119, v0
	v_mov_b32_e32 v128, v0
	v_mov_b32_e32 v129, v0
	v_mov_b32_e32 v130, v0
	v_mov_b32_e32 v131, v0
	v_mov_b32_e32 v132, v0
	v_mov_b32_e32 v133, v0
	v_mov_b32_e32 v134, v0
	v_mov_b32_e32 v135, v0
	v_mov_b32_e32 v144, v0
	v_mov_b32_e32 v145, v0
	v_mov_b32_e32 v146, v0
	v_mov_b32_e32 v147, v0
	v_mov_b32_e32 v148, v0
	v_mov_b32_e32 v149, v0
	v_mov_b32_e32 v150, v0
	v_mov_b32_e32 v151, v0
	s_nop 0
	s_nop 0
	s_nop 0

;   __device__ __forceinline__ bool next(int i,AttnUnit&u)const{ if(i>=2)return false; const int s=vcu&15; u.bh=vcu>>4; u.qb=(i==0)?s:31-s; return true; }
; #define PG8_WAIT_V(n) asm volatile("s_waitcnt vmcnt(" #n ")" ::: "memory")
; #define PG8_BAR __builtin_amdgcn_s_barrier()
; template <class Epi, class Sched, bool ALIGN_EPI = false, bool SP2 = false>
; __device__ __forceinline__ void gemm_phase(PG8_LAS unsigned char* lds, const Gemm g, const Sched& S, const Epi& E) {
;     ...
;     f32x4 acc[2][2][4][2];
; #pragma unroll
;     for (int a = 0; a < 2; ++a)
; #pragma unroll
;         for (int b = 0; b < 2; ++b)
; #pragma unroll
;             for (int m = 0; m < 4; ++m)
; #pragma unroll
;                 for (int n = 0; n < 2; ++n) acc[a][b][m][n] = (f32x4){0.f, 0.f, 0.f, 0.f};
;     bf16x8 At[4][2], B0[2][2], B1[2][2];
;     const char* cA = (const char*)g.A + (size_t)cur.pm * tstep; const char* cB = (const char*)g.Bt + (size_t)cur.pn * tstep;
;     S.a_ready(cur);
;     if constexpr (SP2) {
;         PG8_STAGE(PG8_SB(0, 0), cB, voffB); PG8_STAGE(PG8_SB(0, 1), cB + hstep, voffB); PG8_STAGE(PG8_SA(0, 0), cA, voffA); PG8_STAGE(PG8_SA(0, 1), cA + hstep, voffA);
;         if (wr == 1) PG8_BAR;
;         PG8_WAIT_V(2); PG8_BAR;
;         PG8_STAGE(PG8_SB(1, 0), cB + kstep, voffB); PG8_STAGE(PG8_SA(1, 0), cA + kstep, voffA); PG8_STAGE(PG8_SB(1, 1), cB + hstep + kstep, voffB);
;         PG8_WAIT_V(6); PG8_BAR;
;     } else {
;         PG8_STAGE(PG8_SB(0, 0), cB, voffB); PG8_STAGE(PG8_SA(0, 0), cA, voffA); PG8_STAGE(PG8_SB(0, 1), cB + hstep, voffB); PG8_STAGE(PG8_SA(0, 1), cA + hstep, voffA);
;         if (wr == 1) PG8_BAR;
;         PG8_WAIT_V(4); PG8_BAR;
;         PG8_STAGE(PG8_SB(1, 0), cB + kstep, voffB); PG8_STAGE(PG8_SA(1, 0), cA + kstep, voffA); PG8_STAGE(PG8_SB(1, 1), cB + hstep + kstep, voffB);
;         PG8_WAIT_V(6); PG8_BAR;
;     }
;     for (;;) {
;         const bool has_next = S.next(ui + 1, nxt);
;         const char* nA = has_next ? (const char*)g.A + (size_t)nxt.pm * tstep : cA; const char* nB = has_next ? (const char*)g.Bt + (size_t)nxt.pn * tstep : cB;
;         for (int t = 0; t < nt; t += 2) {
;             const bool last = (t == nt - 2);
;             const char* a1 = cA + (size_t)(t + 1) * kstep;
;             const char* a2 = last ? nA : cA + (size_t)(t + 2) * kstep; const char* b2 = last ? nB : cB + (size_t)(t + 2) * kstep;
.LBB0_3615:
	s_add_u32 s47, s22, 0x100
	v_mov_b32_e32 v4, 0
	s_addc_u32 s48, s23, 0
	s_mov_b32 s49, -2
	v_mov_b32_e32 v5, v4
	v_mov_b32_e32 v6, v4
	v_mov_b32_e32 v7, v4
	v_mov_b32_e32 v0, v4
	v_mov_b32_e32 v1, v4
	v_mov_b32_e32 v2, v4
	v_mov_b32_e32 v3, v4
	v_mov_b32_e32 v20, v4
	v_mov_b32_e32 v21, v4
	v_mov_b32_e32 v22, v4
	v_mov_b32_e32 v23, v4
	v_mov_b32_e32 v16, v4
	v_mov_b32_e32 v17, v4
	v_mov_b32_e32 v18, v4
	v_mov_b32_e32 v19, v4
	v_mov_b32_e32 v36, v4
	v_mov_b32_e32 v37, v4
	v_mov_b32_e32 v38, v4
	v_mov_b32_e32 v39, v4
	v_mov_b32_e32 v32, v4
	v_mov_b32_e32 v33, v4
	v_mov_b32_e32 v34, v4
	v_mov_b32_e32 v35, v4
	v_mov_b32_e32 v52, v4
	v_mov_b32_e32 v53, v4
	v_mov_b32_e32 v54, v4
	v_mov_b32_e32 v55, v4
	v_mov_b32_e32 v48, v4
	v_mov_b32_e32 v49, v4
	v_mov_b32_e32 v50, v4
	v_mov_b32_e32 v51, v4
	v_mov_b32_e32 v12, v4
	v_mov_b32_e32 v13, v4
	v_mov_b32_e32 v14, v4
	v_mov_b32_e32 v15, v4
	v_mov_b32_e32 v8, v4
	v_mov_b32_e32 v9, v4
	v_mov_b32_e32 v10, v4
	v_mov_b32_e32 v11, v4
	v_mov_b32_e32 v28, v4
	v_mov_b32_e32 v29, v4
	v_mov_b32_e32 v30, v4
	v_mov_b32_e32 v31, v4
	v_mov_b32_e32 v24, v4
	v_mov_b32_e32 v25, v4
	v_mov_b32_e32 v26, v4
	v_mov_b32_e32 v27, v4
	v_mov_b32_e32 v44, v4
	v_mov_b32_e32 v45, v4
	v_mov_b32_e32 v46, v4
	v_mov_b32_e32 v47, v4
	v_mov_b32_e32 v40, v4
	v_mov_b32_e32 v41, v4
	v_mov_b32_e32 v42, v4
	v_mov_b32_e32 v43, v4
	v_mov_b32_e32 v60, v4
	v_mov_b32_e32 v61, v4
	v_mov_b32_e32 v62, v4
	v_mov_b32_e32 v63, v4
	v_mov_b32_e32 v56, v4
	v_mov_b32_e32 v57, v4
	v_mov_b32_e32 v58, v4
	v_mov_b32_e32 v59, v4
	v_mov_b32_e32 v68, v4
	v_mov_b32_e32 v69, v4
	v_mov_b32_e32 v70, v4
	v_mov_b32_e32 v71, v4
	v_mov_b32_e32 v64, v4
	v_mov_b32_e32 v65, v4
	v_mov_b32_e32 v66, v4
	v_mov_b32_e32 v67, v4
	v_mov_b32_e32 v84, v4
	v_mov_b32_e32 v85, v4
	v_mov_b32_e32 v86, v4
	v_mov_b32_e32 v87, v4
	v_mov_b32_e32 v80, v4
	v_mov_b32_e32 v81, v4
	v_mov_b32_e32 v82, v4
	v_mov_b32_e32 v83, v4
	v_mov_b32_e32 v100, v4
	v_mov_b32_e32 v101, v4
	v_mov_b32_e32 v102, v4
	v_mov_b32_e32 v103, v4
	v_mov_b32_e32 v96, v4
	v_mov_b32_e32 v97, v4
	v_mov_b32_e32 v98, v4
	v_mov_b32_e32 v99, v4
	v_mov_b32_e32 v112, v4
	v_mov_b32_e32 v113, v4
	v_mov_b32_e32 v114, v4
	v_mov_b32_e32 v115, v4
	v_mov_b32_e32 v116, v4
	v_mov_b32_e32 v117, v4
	v_mov_b32_e32 v118, v4
	v_mov_b32_e32 v119, v4
	v_mov_b32_e32 v76, v4
	v_mov_b32_e32 v77, v4
	v_mov_b32_e32 v78, v4
	v_mov_b32_e32 v79, v4
	v_mov_b32_e32 v72, v4
	v_mov_b32_e32 v73, v4
	v_mov_b32_e32 v74, v4
	v_mov_b32_e32 v75, v4
	v_mov_b32_e32 v92, v4
	v_mov_b32_e32 v93, v4
	v_mov_b32_e32 v94, v4
	v_mov_b32_e32 v95, v4
	v_mov_b32_e32 v88, v4
	v_mov_b32_e32 v89, v4
	v_mov_b32_e32 v90, v4
	v_mov_b32_e32 v91, v4
	v_mov_b32_e32 v104, v4
	v_mov_b32_e32 v105, v4
	v_mov_b32_e32 v106, v4
	v_mov_b32_e32 v107, v4
	v_mov_b32_e32 v108, v4
	v_mov_b32_e32 v109, v4
	v_mov_b32_e32 v110, v4
	v_mov_b32_e32 v111, v4
	v_mov_b32_e32 v120, v4
	v_mov_b32_e32 v121, v4
	v_mov_b32_e32 v122, v4
	v_mov_b32_e32 v123, v4
	v_mov_b32_e32 v124, v4
	v_mov_b32_e32 v125, v4
	v_mov_b32_e32 v126, v4
	v_mov_b32_e32 v127, v4
	s_nop 0
	s_nop 0
	s_nop 0
	s_nop 0
	s_nop 0
	s_nop 0
	s_nop 0
	s_nop 0
